# EpiMerge: hoist 16 serialized gate loads (two batches, counted vmcnt); EpiUp: one unconditional vmcnt(0) per half replaces 16 per-block vmcnt ladders; EpiRes hoist kept
# speedup vs baseline: 1.0095x; 1.0095x over previous
; __device__ __forceinline__ void load_rs8(const float* ss, int t0, int fq, float (&rs)[8], int tmax) {
; #pragma unroll
;     for (int j = 0; j < 8; ++j) { int t = t0 + j; t = t < 0 ? 0 : (t > tmax ? tmax : t);
;         const f32x4 p = *(const f32x4*)(ss + (size_t)t * 16 + 4 * fq); float s = (p.x + p.y) + (p.z + p.w);
;         s += __shfl_xor(s, 16); s += __shfl_xor(s, 32); rs[j] = __builtin_amdgcn_rsqf(s * (1.0f / DMOD) + EPS); }
;     __device__ __forceinline__ void operator()(f32x4 (&acc)[2][2][4][2], const Unit& u, int wr, int wc, int fr, int fq) const {
;         const int t0 = u.pm * 252 - 1 + wr * 126 + fr * 8;
;         { float rs[8]; load_rs8(ss, t0, fq, rs, M_TOK - 1);
; #pragma unroll
;           for (int ai = 0; ai < 2; ++ai)
; #pragma unroll
;             for (int m = 0; m < 4; ++m)
; #pragma unroll
;                 for (int bj = 0; bj < 2; ++bj)
; #pragma unroll
;                     for (int n = 0; n < 2; ++n) acc[ai][bj][m][n] = acc[ai][bj][m][n] * rs[4 * ai + m]; }
;         unsigned vmask = 0, smask = 0, emask = 0;
; #pragma unroll
;         for (int j = 0; j < 8; ++j) { const int t = t0 + j, loc = fr * 8 + j;
;             if (loc >= 1 && loc <= 126 && t < M_TOK) vmask |= 1u << j;
;             const int sm = (t < NPROMPT) ? (SEQ_P - 1) : (SEQ_S - 1);
;             if ((t & sm) == 0) smask |= 1u << j;
;             if ((t & sm) == sm) emask |= 1u << j; }
; #pragma unroll
;         for (int n = 0; n < 2; ++n) {
;             const int cg_ = 128 * u.pn + 32 * wc + 8 * fq + 4 * n;
;             const f32x4 w0g = *(const f32x4*)(cw + cg_), w1g = *(const f32x4*)(cw + 4096 + cg_), w2g = *(const f32x4*)(cw + 8192 + cg_), bg = *(const f32x4*)(cb + cg_);
;             const f32x4 w0v = *(const f32x4*)(cw + 2048 + cg_), w1v = *(const f32x4*)(cw + 4096 + 2048 + cg_), w2v = *(const f32x4*)(cw + 8192 + 2048 + cg_), bv = *(const f32x4*)(cb + 2048 + cg_);
.LBB0_120:
	s_mul_i32 s0, s50, 0xfc
	v_add_u32_e32 v182, s0, v236
	v_min_u32_e32 v0, 0x17fff, v182
	v_lshlrev_b32_e32 v0, 4, v0
	v_cmp_lt_i32_e32 vcc, -1, v182
	v_and_b32_e32 v93, 64, v219
	v_xor_b32_e32 v92, 16, v219
	v_cndmask_b32_e32 v0, 0, v0, vcc
	v_lshlrev_b32_e32 v0, 2, v0
	v_lshl_add_u64 v[90:91], v[174:175], 0, v[0:1]
	v_min_i32_e32 v0, 0x17ffe, v182
	v_lshl_add_u32 v0, v0, 4, 16
	v_cmp_lt_i32_e32 vcc, -2, v182
	global_load_dwordx4 v[114:117], v[90:91], off
	v_xor_b32_e32 v94, 32, v219
	v_cndmask_b32_e32 v0, 0, v0, vcc
	v_lshl_add_u64 v[90:91], v[0:1], 2, v[174:175]
	global_load_dwordx4 v[118:121], v[90:91], off
	v_min_i32_e32 v0, 0x17ffd, v182
	v_lshl_add_u32 v0, v0, 4, 32
	v_cmp_lt_i32_e32 vcc, -3, v182
	v_lshl_or_b32 v180, s42, 7, v237
	v_ashrrev_i32_e32 v181, 31, v180
	v_cndmask_b32_e32 v0, 0, v0, vcc
	v_lshl_add_u64 v[90:91], v[0:1], 2, v[174:175]
	global_load_dwordx4 v[196:199], v[90:91], off
	v_min_i32_e32 v0, 0x17ffc, v182
	v_lshl_add_u32 v0, v0, 4, 48
	v_cmp_lt_i32_e32 vcc, -4, v182
	v_readlane_b32 s0, v255, 12
	v_lshlrev_b64 v[224:225], 2, v[180:181]
	v_cndmask_b32_e32 v0, 0, v0, vcc
	v_lshl_add_u64 v[90:91], v[0:1], 2, v[174:175]
	v_min_i32_e32 v0, 0x17ffb, v182
	global_load_dwordx4 v[162:165], v[90:91], off
	v_lshl_add_u32 v0, v0, 4, 64
	v_cmp_lt_i32_e32 vcc, -5, v182
	v_readlane_b32 s1, v255, 13
	s_waitcnt vmcnt(0)
	v_mov_b32_e32 v188, v115
	v_cndmask_b32_e32 v0, 0, v0, vcc
	v_lshl_add_u64 v[90:91], v[0:1], 2, v[174:175]
	v_min_i32_e32 v0, 0x17ffa, v182
	global_load_dwordx4 v[200:203], v[90:91], off
	v_min_i32_e32 v90, 0x17ff9, v182
	v_lshl_add_u32 v0, v0, 4, v220
	v_cmp_lt_i32_e32 vcc, -6, v182
	v_min_i32_e32 v91, 0x17ff8, v182
	v_lshl_add_u32 v95, v90, 4, v221
	v_cndmask_b32_e32 v0, 0, v0, vcc
	v_cmp_lt_i32_e32 vcc, -7, v182
	v_lshl_add_u32 v96, v91, 4, v222
	v_lshl_add_u64 v[90:91], v[0:1], 2, v[174:175]
	v_cndmask_b32_e32 v0, 0, v95, vcc
	v_cmp_lt_i32_e32 vcc, -8, v182
	global_load_dwordx4 v[204:207], v[90:91], off
	v_lshl_add_u64 v[90:91], v[0:1], 2, v[174:175]
	v_cndmask_b32_e32 v0, 0, v96, vcc
	global_load_dwordx4 v[208:211], v[90:91], off
	v_lshl_add_u64 v[90:91], v[0:1], 2, v[174:175]
	global_load_dwordx4 v[212:215], v[90:91], off
	v_add_u32_e32 v0, 64, v93
	v_cmp_lt_i32_e32 vcc, v92, v0
	v_mov_b32_e32 v189, v116
	v_mov_b32_e32 v115, v117
	v_cndmask_b32_e32 v90, v219, v92, vcc
	v_cmp_lt_i32_e32 vcc, v94, v0
	v_pk_add_f32 v[114:115], v[188:189], v[114:115]
	v_mov_b32_e32 v116, v119
	v_cndmask_b32_e32 v0, v219, v94, vcc
	v_mov_b32_e32 v117, v120
	v_mov_b32_e32 v119, v121
	v_lshlrev_b32_e32 v183, 2, v90
	v_lshlrev_b32_e32 v228, 2, v0
	v_add_f32_e32 v0, v114, v115
	v_pk_add_f32 v[114:115], v[116:117], v[118:119]
	ds_bpermute_b32 v118, v183, v0
	v_add_f32_e32 v119, v114, v115
	v_lshl_add_u64 v[184:185], s[0:1], 0, v[224:225]
	v_readlane_b32 s0, v255, 4
	ds_bpermute_b32 v120, v183, v119
	v_readlane_b32 s1, v255, 5
	v_mov_b32_e32 v116, v197
	v_mov_b32_e32 v117, v198
	v_lshl_add_u64 v[90:91], s[0:1], 0, v[224:225]
	v_readlane_b32 s0, v255, 6
	v_readlane_b32 s1, v255, 7
	v_mov_b32_e32 v197, v199
	s_waitcnt lgkmcnt(1)
	v_add_f32_e32 v0, v0, v118
	v_lshl_add_u64 v[92:93], s[0:1], 0, v[224:225]
	v_readlane_b32 s0, v255, 16
	v_readlane_b32 s1, v255, 17
	v_pk_add_f32 v[114:115], v[116:117], v[196:197]
	ds_bpermute_b32 v116, v228, v0
	s_waitcnt lgkmcnt(1)
	v_add_f32_e32 v117, v119, v120
	v_lshl_add_u64 v[186:187], s[0:1], 0, v[224:225]
	v_readlane_b32 s0, v255, 8
	ds_bpermute_b32 v118, v228, v117
	v_readlane_b32 s1, v255, 9
	s_waitcnt lgkmcnt(1)
	v_add_f32_e32 v0, v0, v116
	v_add_f32_e32 v189, v114, v115
	v_lshl_add_u64 v[94:95], s[0:1], 0, v[224:225]
	v_readlane_b32 s0, v255, 10
	v_readlane_b32 s1, v255, 11
	v_fmamk_f32 v0, v0, 0x3a800000, v218
	s_waitcnt lgkmcnt(0)
	v_add_f32_e32 v114, v117, v118
	v_lshl_add_u64 v[96:97], s[0:1], 0, v[224:225]
	v_readlane_b32 s0, v255, 14
	global_load_dwordx4 v[98:101], v[184:185], off
	global_load_dwordx4 v[110:113], v[90:91], off
	global_load_dwordx4 v[102:105], v[92:93], off
	global_load_dwordx4 v[106:109], v[186:187], off
	s_nop 0
	global_load_dwordx4 v[90:93], v[94:95], off
	s_nop 0
	global_load_dwordx4 v[94:97], v[96:97], off
	v_readlane_b32 s1, v255, 15
	v_rsq_f32_e32 v196, v0
	v_fmamk_f32 v0, v114, 0x3a800000, v218
	v_lshl_add_u64 v[114:115], s[0:1], 0, v[224:225]
	v_readlane_b32 s0, v255, 18
	v_readlane_b32 s1, v255, 19
	global_load_dwordx4 v[114:117], v[114:115], off
	v_mov_b32_e32 v198, v163
	v_lshl_add_u64 v[118:119], s[0:1], 0, v[224:225]
	global_load_dwordx4 v[118:121], v[118:119], off
	v_mov_b32_e32 v199, v164
	v_mov_b32_e32 v163, v165
	v_pk_add_f32 v[162:163], v[198:199], v[162:163]
	v_rsq_f32_e32 v188, v0
	v_add_f32_e32 v0, v162, v163
	ds_bpermute_b32 v164, v183, v0
	s_waitcnt vmcnt(11)
	v_mov_b32_e32 v162, v201
	v_mov_b32_e32 v163, v202
	v_mov_b32_e32 v201, v203
	v_pk_add_f32 v[162:163], v[162:163], v[200:201]
	s_waitcnt lgkmcnt(0)
	v_add_f32_e32 v241, v0, v164
	v_add_f32_e32 v162, v162, v163
	ds_bpermute_b32 v163, v183, v162
	ds_bpermute_b32 v197, v183, v189
	s_mov_b32 s0, 0x18000
	v_cmp_gt_i32_e32 vcc, s0, v182
	v_readlane_b32 s0, v255, 0
	s_waitcnt lgkmcnt(1)
	v_add_f32_e32 v239, v162, v163
	s_waitcnt vmcnt(10)
	v_mov_b32_e32 v162, v205
	v_mov_b32_e32 v163, v206
	v_mov_b32_e32 v205, v207
	s_waitcnt vmcnt(8)
	v_mov_b32_e32 v164, v213
	v_mov_b32_e32 v165, v214
	v_mov_b32_e32 v213, v215
	v_pk_add_f32 v[164:165], v[164:165], v[212:213]
	v_pk_add_f32 v[162:163], v[162:163], v[204:205]
	v_add_f32_e32 v164, v164, v165
	ds_bpermute_b32 v165, v183, v164
	v_add_f32_e32 v0, v162, v163
	v_mov_b32_e32 v162, v209
	v_mov_b32_e32 v163, v210
	v_mov_b32_e32 v209, v211
	v_pk_add_f32 v[162:163], v[162:163], v[208:209]
	s_waitcnt lgkmcnt(0)
;     __device__ __forceinline__ void operator()(f32x4 (&acc)[2][2][4][2], const Unit& u, int wr, int wc, int fr, int fq) const {
;     ...
;                     for (int n = 0; n < 2; ++n) acc[ai][bj][m][n] = acc[ai][bj][m][n] * rs[4 * ai + m]; }
;         unsigned vmask = 0, smask = 0, emask = 0;
; #pragma unroll
;         for (int j = 0; j < 8; ++j) { const int t = t0 + j, loc = fr * 8 + j;
;             if (loc >= 1 && loc <= 126 && t < M_TOK) vmask |= 1u << j;
;             const int sm = (t < NPROMPT) ? (SEQ_P - 1) : (SEQ_S - 1);
;             if ((t & sm) == 0) smask |= 1u << j;
;             if ((t & sm) == sm) emask |= 1u << j; }
; #pragma unroll
;         for (int n = 0; n < 2; ++n) {
;             const int cg_ = 128 * u.pn + 32 * wc + 8 * fq + 4 * n;
;             const f32x4 w0g = *(const f32x4*)(cw + cg_), w1g = *(const f32x4*)(cw + 4096 + cg_), w2g = *(const f32x4*)(cw + 8192 + cg_), bg = *(const f32x4*)(cb + cg_);
;             const f32x4 w0v = *(const f32x4*)(cw + 2048 + cg_), w1v = *(const f32x4*)(cw + 4096 + 2048 + cg_), w2v = *(const f32x4*)(cw + 8192 + 2048 + cg_), bv = *(const f32x4*)(cb + 2048 + cg_);
;             float h[8][4];
; #pragma unroll
;             for (int i = 0; i < 4; ++i) {
;                 float ag[8], av[8];
; #pragma unroll
;                 for (int j = 0; j < 8; ++j) { ag[j] = acc[j >> 2][0][j & 3][n][i]; av[j] = acc[j >> 2][1][j & 3][n][i]; }
;                 const float lg = dpp_shr1(ag[7]), rg = dpp_shl1(ag[0]), lv = dpp_shr1(av[7]), rv = dpp_shl1(av[0]);
; #pragma unroll
;                 for (int j = 0; j < 8; ++j) {
;                     float Lg = j == 0 ? lg : ag[j == 0 ? 0 : j - 1], Rg = j == 7 ? rg : ag[j == 7 ? 7 : j + 1];
;                     float Lv = j == 0 ? lv : av[j == 0 ? 0 : j - 1], Rv = j == 7 ? rv : av[j == 7 ? 7 : j + 1];
;                     if ((smask >> j) & 1u) { Lg = 0.f; Lv = 0.f; }
;                     if ((emask >> j) & 1u) { Rg = 0.f; Rv = 0.f; }
;                     const float cgv = w0g[i] * Lg + w1g[i] * ag[j] + w2g[i] * Rg + bg[i];
;                     const float cvv = w0v[i] * Lv + w1v[i] * av[j] + w2v[i] * Rv + bv[i];
;                     h[j][i] = gelu_t(cgv) * cvv;
;                 }
;             }
; #pragma unroll
;             for (int j = 0; j < 8; ++j) if ((vmask >> j) & 1u) { u32x2 w; w.x = cvt_pk_bf16(h[j][0], h[j][1]); w.y = cvt_pk_bf16(h[j][2], h[j][3]);
	v_add_f32_e32 v164, v164, v165
	v_add_f32_e32 v162, v162, v163
	v_add_f32_e32 v200, v189, v197
	ds_bpermute_b32 v189, v183, v0
	ds_bpermute_b32 v163, v183, v162
	ds_bpermute_b32 v165, v228, v164
	v_readlane_b32 s1, v255, 1
	ds_bpermute_b32 v201, v228, v200
	s_waitcnt lgkmcnt(3)
	v_add_f32_e32 v189, v0, v189
	s_waitcnt lgkmcnt(2)
	v_add_f32_e32 v0, v162, v163
	s_waitcnt lgkmcnt(1)
	v_add_f32_e32 v162, v164, v165
	ds_bpermute_b32 v197, v228, v189
	ds_bpermute_b32 v163, v228, v0
	v_fmamk_f32 v162, v162, 0x3a800000, v218
	v_rsq_f32_e32 v162, v162
	ds_bpermute_b32 v242, v228, v241
	ds_bpermute_b32 v240, v228, v239
	s_and_b64 s[82:83], s[0:1], vcc
	s_mov_b32 s0, 0x8000
	v_cmp_gt_i32_e32 vcc, s0, v182
	s_waitcnt lgkmcnt(3)
	v_pk_mul_f32 v[202:203], v[152:153], v[196:197] op_sel_hi:[1,0]
	s_waitcnt lgkmcnt(2)
	v_pk_mul_f32 v[152:153], v[138:139], v[162:163] op_sel_hi:[1,0]
	v_cndmask_b32_e32 v138, v223, v227, vcc
	v_pk_mul_f32 v[210:211], v[160:161], v[196:197] op_sel_hi:[1,0]
	v_pk_mul_f32 v[214:215], v[158:159], v[196:197] op_sel_hi:[1,0]
	v_pk_mul_f32 v[212:213], v[150:151], v[196:197] op_sel_hi:[1,0]
	v_pk_mul_f32 v[206:207], v[146:147], v[188:189] op_sel_hi:[1,0]
	v_pk_mul_f32 v[164:165], v[148:149], v[188:189] op_sel_hi:[1,0]
	v_pk_mul_f32 v[148:149], v[144:145], v[162:163] op_sel_hi:[1,0]
	v_pk_mul_f32 v[158:159], v[142:143], v[162:163] op_sel_hi:[1,0]
	v_pk_mul_f32 v[146:147], v[140:141], v[162:163] op_sel_hi:[1,0]
	v_or_b32_e32 v138, v138, v182
	v_pk_mul_f32 v[208:209], v[154:155], v[188:189] op_sel_hi:[1,0]
	v_pk_mul_f32 v[198:199], v[156:157], v[188:189] op_sel_hi:[1,0]
	v_cmp_eq_u32_e64 s[42:43], -1, v138
	v_mov_b32_dpp v140, v158 row_shr:1 row_mask:0xf bank_mask:0xf bound_ctrl:1
	v_mov_b32_dpp v160, v214 row_shl:1 row_mask:0xf bank_mask:0xf bound_ctrl:1
	v_mov_b32_dpp v138, v152 row_shr:1 row_mask:0xf bank_mask:0xf bound_ctrl:1
	v_mov_b32_dpp v154, v212 row_shl:1 row_mask:0xf bank_mask:0xf bound_ctrl:1
	v_mov_b32_dpp v141, v159 row_shr:1 row_mask:0xf bank_mask:0xf bound_ctrl:1
	v_mov_b32_dpp v161, v215 row_shl:1 row_mask:0xf bank_mask:0xf bound_ctrl:1
	v_mov_b32_dpp v139, v153 row_shr:1 row_mask:0xf bank_mask:0xf bound_ctrl:1
	v_mov_b32_dpp v155, v213 row_shl:1 row_mask:0xf bank_mask:0xf bound_ctrl:1
	v_mov_b32_dpp v144, v148 row_shr:1 row_mask:0xf bank_mask:0xf bound_ctrl:1
	v_mov_b32_dpp v156, v210 row_shl:1 row_mask:0xf bank_mask:0xf bound_ctrl:1
	v_mov_b32_dpp v142, v146 row_shr:1 row_mask:0xf bank_mask:0xf bound_ctrl:1
	v_mov_b32_dpp v150, v202 row_shl:1 row_mask:0xf bank_mask:0xf bound_ctrl:1
	v_mov_b32_dpp v145, v149 row_shr:1 row_mask:0xf bank_mask:0xf bound_ctrl:1
	v_mov_b32_dpp v157, v211 row_shl:1 row_mask:0xf bank_mask:0xf bound_ctrl:1
	v_mov_b32_dpp v143, v147 row_shr:1 row_mask:0xf bank_mask:0xf bound_ctrl:1
	v_mov_b32_dpp v151, v203 row_shl:1 row_mask:0xf bank_mask:0xf bound_ctrl:1
	v_ashrrev_i32_e32 v183, 31, v182
	s_waitcnt vmcnt(0)
	s_and_saveexec_b64 s[0:1], s[82:83]
	s_cbranch_execz .LBB0_122
	v_pk_mul_f32 v[144:145], v[100:101], v[144:145]
	v_cndmask_b32_e64 v225, v199, 0, s[42:43]
	v_cndmask_b32_e64 v224, v198, 0, s[42:43]
	v_pk_fma_f32 v[144:145], v[210:211], v[112:113], v[144:145]
	v_pk_mul_f32 v[142:143], v[92:93], v[142:143]
	v_pk_fma_f32 v[144:145], v[224:225], v[104:105], v[144:145]
	v_cndmask_b32_e64 v205, v165, 0, s[42:43]
	v_pk_add_f32 v[144:145], v[108:109], v[144:145]
	v_cndmask_b32_e64 v204, v164, 0, s[42:43]
	v_mul_f32_e32 v224, 0x3d122279, v145
	v_fmaak_f32 v224, v145, v224, 0x3f4c422a
	v_mul_f32_e32 v225, 0x3d122279, v144
	v_mul_f32_e32 v224, v145, v224
	v_fmaak_f32 v225, v144, v225, 0x3f4c422a
	v_mul_f32_e32 v224, 0xc038aa3b, v224
	v_mul_f32_e32 v225, v144, v225
	v_exp_f32_e32 v224, v224
	v_mul_f32_e32 v225, 0xc038aa3b, v225
	v_exp_f32_e32 v228, v225
	v_pk_fma_f32 v[142:143], v[202:203], v[96:97], v[142:143]
	v_pk_mul_f32 v[140:141], v[98:99], v[140:141]
	v_pk_fma_f32 v[142:143], v[204:205], v[116:117], v[142:143]
	v_cndmask_b32_e64 v205, v209, 0, s[42:43]
	v_cndmask_b32_e64 v204, v208, 0, s[42:43]
	v_pk_fma_f32 v[140:141], v[214:215], v[110:111], v[140:141]
	v_add_f32_e32 v224, 1.0, v224
	v_pk_fma_f32 v[140:141], v[204:205], v[102:103], v[140:141]
	v_rcp_f32_e32 v225, v224
	v_pk_add_f32 v[140:141], v[106:107], v[140:141]
	v_add_f32_e32 v224, 1.0, v228
	v_mul_f32_e32 v204, 0x3d122279, v141
	v_rcp_f32_e32 v224, v224
	v_fmaak_f32 v204, v141, v204, 0x3f4c422a
	v_mul_f32_e32 v205, 0x3d122279, v140
	v_mul_f32_e32 v204, v141, v204
	v_fmaak_f32 v205, v140, v205, 0x3f4c422a
	v_mul_f32_e32 v204, 0xc038aa3b, v204
	v_mul_f32_e32 v205, v140, v205
	v_exp_f32_e32 v204, v204
	v_mul_f32_e32 v205, 0xc038aa3b, v205
	v_pk_mul_f32 v[144:145], v[144:145], v[224:225]
	v_exp_f32_e32 v224, v205
	v_add_f32_e32 v204, 1.0, v204
	v_rcp_f32_e32 v205, v204
	v_pk_add_f32 v[142:143], v[120:121], v[142:143]
	v_add_f32_e32 v204, 1.0, v224
	v_rcp_f32_e32 v204, v204
	v_pk_mul_f32 v[138:139], v[90:91], v[138:139]
	v_pk_mul_f32 v[142:143], v[142:143], v[144:145]
	v_cndmask_b32_e64 v145, v207, 0, s[42:43]
	v_cndmask_b32_e64 v144, v206, 0, s[42:43]
	v_pk_fma_f32 v[138:139], v[212:213], v[94:95], v[138:139]
	v_pk_mul_f32 v[140:141], v[140:141], v[204:205]
	v_pk_fma_f32 v[138:139], v[144:145], v[114:115], v[138:139]
	s_nop 0
	v_pk_add_f32 v[138:139], v[118:119], v[138:139]
	s_nop 0
	v_pk_mul_f32 v[138:139], v[138:139], v[140:141]
	v_lshlrev_b64 v[140:141], 12, v[182:183]
	v_lshl_add_u64 v[140:141], s[70:71], 0, v[140:141]
	v_cvt_pk_bf16_f32 v138, v138, v139
	v_cvt_pk_bf16_f32 v139, v142, v143
	v_lshl_add_u64 v[140:141], v[180:181], 1, v[140:141]
	global_store_dwordx2 v[140:141], v[138:139], off
;     __device__ __forceinline__ void operator()(f32x4 (&acc)[2][2][4][2], const Unit& u, int wr, int wc, int fr, int fq) const {
;     ...
;                     for (int n = 0; n < 2; ++n) acc[ai][bj][m][n] = acc[ai][bj][m][n] * rs[4 * ai + m]; }
;         unsigned vmask = 0, smask = 0, emask = 0;
; #pragma unroll
;         for (int j = 0; j < 8; ++j) { const int t = t0 + j, loc = fr * 8 + j;
;             if (loc >= 1 && loc <= 126 && t < M_TOK) vmask |= 1u << j;
;             const int sm = (t < NPROMPT) ? (SEQ_P - 1) : (SEQ_S - 1);
;             if ((t & sm) == 0) smask |= 1u << j;
;             if ((t & sm) == sm) emask |= 1u << j; }
; #pragma unroll
;         for (int n = 0; n < 2; ++n) {
;             const int cg_ = 128 * u.pn + 32 * wc + 8 * fq + 4 * n;
;             const f32x4 w0g = *(const f32x4*)(cw + cg_), w1g = *(const f32x4*)(cw + 4096 + cg_), w2g = *(const f32x4*)(cw + 8192 + cg_), bg = *(const f32x4*)(cb + cg_);
;             const f32x4 w0v = *(const f32x4*)(cw + 2048 + cg_), w1v = *(const f32x4*)(cw + 4096 + 2048 + cg_), w2v = *(const f32x4*)(cw + 8192 + 2048 + cg_), bv = *(const f32x4*)(cb + 2048 + cg_);
;             float h[8][4];
; #pragma unroll
;             for (int i = 0; i < 4; ++i) {
;                 float ag[8], av[8];
; #pragma unroll
;                 for (int j = 0; j < 8; ++j) { ag[j] = acc[j >> 2][0][j & 3][n][i]; av[j] = acc[j >> 2][1][j & 3][n][i]; }
;                 const float lg = dpp_shr1(ag[7]), rg = dpp_shl1(ag[0]), lv = dpp_shr1(av[7]), rv = dpp_shl1(av[0]);
; #pragma unroll
;                 for (int j = 0; j < 8; ++j) {
;                     float Lg = j == 0 ? lg : ag[j == 0 ? 0 : j - 1], Rg = j == 7 ? rg : ag[j == 7 ? 7 : j + 1];
;                     float Lv = j == 0 ? lv : av[j == 0 ? 0 : j - 1], Rv = j == 7 ? rv : av[j == 7 ? 7 : j + 1];
;                     if ((smask >> j) & 1u) { Lg = 0.f; Lv = 0.f; }
;                     if ((emask >> j) & 1u) { Rg = 0.f; Rv = 0.f; }
;                     const float cgv = w0g[i] * Lg + w1g[i] * ag[j] + w2g[i] * Rg + bg[i];
;                     const float cvv = w0v[i] * Lv + w1v[i] * av[j] + w2v[i] * Rv + bv[i];
;                     h[j][i] = gelu_t(cgv) * cvv;
;                 }
;             }
; #pragma unroll
;             for (int j = 0; j < 8; ++j) if ((vmask >> j) & 1u) { u32x2 w; w.x = cvt_pk_bf16(h[j][0], h[j][1]); w.y = cvt_pk_bf16(h[j][2], h[j][3]);
.LBB0_122:
	s_or_b64 exec, exec, s[0:1]
	v_add_f32_e32 v138, v200, v201
	v_fmamk_f32 v138, v138, 0x3a800000, v218
	v_rsq_f32_e32 v138, v138
	s_mov_b32 s0, 0x17fff
	v_cmp_gt_i32_e64 s[56:57], s0, v182
	s_movk_i32 s0, 0x7fff
	v_cmp_gt_i32_e32 vcc, s0, v182
	v_pk_mul_f32 v[200:201], v[130:131], v[138:139] op_sel_hi:[1,0]
	v_add_u32_e32 v130, 1, v182
	v_cndmask_b32_e32 v131, v217, v226, vcc
	v_and_b32_e32 v131, v131, v130
	v_pk_mul_f32 v[142:143], v[136:137], v[138:139] op_sel_hi:[1,0]
	v_pk_mul_f32 v[204:205], v[134:135], v[138:139] op_sel_hi:[1,0]
	v_pk_mul_f32 v[132:133], v[132:133], v[138:139] op_sel_hi:[1,0]
	v_cmp_eq_u32_e32 vcc, 0, v131
	v_ashrrev_i32_e32 v131, 31, v130
	s_and_saveexec_b64 s[0:1], s[56:57]
	s_cbranch_execz .LBB0_124
	v_cndmask_b32_e64 v135, v215, 0, vcc
	v_cndmask_b32_e64 v134, v214, 0, vcc
	v_pk_mul_f32 v[136:137], v[208:209], v[110:111]
	v_cndmask_b32_e64 v141, v213, 0, vcc
	v_pk_fma_f32 v[134:135], v[134:135], v[98:99], v[136:137]
	v_cndmask_b32_e64 v140, v212, 0, vcc
	v_pk_fma_f32 v[134:135], v[204:205], v[102:103], v[134:135]
	v_pk_mul_f32 v[144:145], v[206:207], v[94:95]
	v_pk_add_f32 v[134:135], v[106:107], v[134:135]
	v_pk_fma_f32 v[140:141], v[140:141], v[90:91], v[144:145]
	v_mul_f32_e32 v136, 0x3d122279, v134
	v_mul_f32_e32 v137, 0x3d122279, v135
	v_fmaak_f32 v136, v134, v136, 0x3f4c422a
	v_fmaak_f32 v137, v135, v137, 0x3f4c422a
	v_mul_f32_e32 v136, v134, v136
	v_mul_f32_e32 v137, v135, v137
	v_mul_f32_e32 v136, 0xc038aa3b, v136
	v_mul_f32_e32 v137, 0xc038aa3b, v137
	v_exp_f32_e32 v136, v136
	v_exp_f32_e32 v137, v137
	v_pk_fma_f32 v[140:141], v[200:201], v[114:115], v[140:141]
	v_cndmask_b32_e64 v145, v203, 0, vcc
	v_add_f32_e32 v136, 1.0, v136
	v_add_f32_e32 v137, 1.0, v137
	v_rcp_f32_e32 v136, v136
	v_rcp_f32_e32 v137, v137
	v_pk_add_f32 v[140:141], v[118:119], v[140:141]
	v_cndmask_b32_e64 v144, v202, 0, vcc
	v_pk_mul_f32 v[202:203], v[164:165], v[96:97]
	v_pk_mul_f32 v[134:135], v[134:135], v[136:137]
	v_cndmask_b32_e64 v137, v211, 0, vcc
	v_pk_mul_f32 v[134:135], v[140:141], v[134:135]
	v_cndmask_b32_e64 v136, v210, 0, vcc
	v_pk_mul_f32 v[140:141], v[198:199], v[112:113]
	v_pk_fma_f32 v[144:145], v[144:145], v[92:93], v[202:203]
	v_pk_fma_f32 v[136:137], v[136:137], v[100:101], v[140:141]
	v_pk_fma_f32 v[144:145], v[132:133], v[116:117], v[144:145]
	v_pk_fma_f32 v[136:137], v[142:143], v[104:105], v[136:137]
	v_pk_add_f32 v[144:145], v[120:121], v[144:145]
	v_pk_add_f32 v[136:137], v[108:109], v[136:137]
	v_cvt_pk_bf16_f32 v134, v134, v135
	v_mul_f32_e32 v139, 0x3d122279, v136
	v_fmaak_f32 v139, v136, v139, 0x3f4c422a
	v_mul_f32_e32 v139, v136, v139
	v_mul_f32_e32 v139, 0xc038aa3b, v139
	v_exp_f32_e32 v139, v139
	s_nop 0
	v_add_f32_e32 v139, 1.0, v139
	v_rcp_f32_e32 v140, v139
	v_mul_f32_e32 v139, 0x3d122279, v137
	v_fmaak_f32 v139, v137, v139, 0x3f4c422a
	v_mul_f32_e32 v139, v137, v139
	v_mul_f32_e32 v139, 0xc038aa3b, v139
	v_exp_f32_e32 v139, v139
	s_nop 0
	v_add_f32_e32 v139, 1.0, v139
	v_rcp_f32_e32 v141, v139
	s_nop 0
	v_pk_mul_f32 v[136:137], v[136:137], v[140:141]
	s_nop 0
	v_pk_mul_f32 v[136:137], v[144:145], v[136:137]
	s_nop 0
	v_cvt_pk_bf16_f32 v135, v136, v137
	v_lshlrev_b64 v[136:137], 12, v[130:131]
	v_lshl_add_u64 v[136:137], s[70:71], 0, v[136:137]
	v_lshl_add_u64 v[136:137], v[180:181], 1, v[136:137]
	global_store_dwordx2 v[136:137], v[134:135], off
.LBB0_124:
	s_or_b64 exec, exec, s[0:1]
	s_waitcnt lgkmcnt(1)
	v_add_f32_e32 v134, v241, v242
	v_fmamk_f32 v134, v134, 0x3a800000, v218
	v_rsq_f32_e32 v136, v134
	s_mov_b32 s0, 0x17ffe
	v_cmp_gt_i32_e64 s[58:59], s0, v182
	s_movk_i32 s0, 0x7ffe
	v_cmp_gt_i32_e64 s[0:1], s0, v182
	v_pk_mul_f32 v[144:145], v[122:123], v[136:137] op_sel_hi:[1,0]
	v_add_u32_e32 v122, 2, v182
	v_cndmask_b32_e64 v123, v223, v227, s[0:1]
	v_or_b32_e32 v123, v123, v122
	v_pk_mul_f32 v[134:135], v[128:129], v[136:137] op_sel_hi:[1,0]
	v_pk_mul_f32 v[202:203], v[126:127], v[136:137] op_sel_hi:[1,0]
	v_pk_mul_f32 v[128:129], v[124:125], v[136:137] op_sel_hi:[1,0]
	v_cmp_eq_u32_e64 s[44:45], -1, v123
	v_ashrrev_i32_e32 v123, 31, v122
	s_and_saveexec_b64 s[0:1], s[58:59]
	s_cbranch_execz .LBB0_126
	v_pk_mul_f32 v[126:127], v[204:205], v[110:111]
	v_cndmask_b32_e64 v125, v203, 0, s[44:45]
	v_cndmask_b32_e64 v124, v202, 0, s[44:45]
	v_pk_fma_f32 v[126:127], v[208:209], v[98:99], v[126:127]
	v_pk_mul_f32 v[208:209], v[200:201], v[94:95]
	v_pk_fma_f32 v[124:125], v[124:125], v[102:103], v[126:127]
	v_cndmask_b32_e64 v141, v145, 0, s[44:45]
	v_pk_add_f32 v[124:125], v[106:107], v[124:125]
	v_cndmask_b32_e64 v140, v144, 0, s[44:45]
	v_mul_f32_e32 v126, 0x3d122279, v124
	v_mul_f32_e32 v127, 0x3d122279, v125
	v_fmaak_f32 v126, v124, v126, 0x3f4c422a
	v_fmaak_f32 v127, v125, v127, 0x3f4c422a
	v_mul_f32_e32 v126, v124, v126
	v_mul_f32_e32 v127, v125, v127
	v_mul_f32_e32 v126, 0xc038aa3b, v126
	v_mul_f32_e32 v127, 0xc038aa3b, v127
	v_exp_f32_e32 v126, v126
	v_exp_f32_e32 v127, v127
	v_pk_fma_f32 v[206:207], v[206:207], v[90:91], v[208:209]
	v_add_f32_e32 v126, 1.0, v126
	v_add_f32_e32 v127, 1.0, v127
	v_rcp_f32_e32 v126, v126
	v_rcp_f32_e32 v127, v127
	v_pk_fma_f32 v[140:141], v[140:141], v[114:115], v[206:207]
	v_pk_mul_f32 v[206:207], v[132:133], v[96:97]
	v_pk_add_f32 v[140:141], v[118:119], v[140:141]
	v_pk_mul_f32 v[124:125], v[124:125], v[126:127]
	v_cndmask_b32_e64 v127, v135, 0, s[44:45]
	v_pk_mul_f32 v[124:125], v[140:141], v[124:125]
	v_pk_mul_f32 v[140:141], v[142:143], v[112:113]
	v_cndmask_b32_e64 v126, v134, 0, s[44:45]
	v_pk_fma_f32 v[140:141], v[198:199], v[100:101], v[140:141]
	v_cndmask_b32_e64 v199, v129, 0, s[44:45]
	v_pk_fma_f32 v[126:127], v[126:127], v[104:105], v[140:141]
	v_cndmask_b32_e64 v198, v128, 0, s[44:45]
	v_pk_add_f32 v[126:127], v[108:109], v[126:127]
	v_pk_fma_f32 v[164:165], v[164:165], v[92:93], v[206:207]
	v_mul_f32_e32 v137, 0x3d122279, v126
	v_fmaak_f32 v137, v126, v137, 0x3f4c422a
	v_mul_f32_e32 v137, v126, v137
	v_mul_f32_e32 v137, 0xc038aa3b, v137
	v_exp_f32_e32 v137, v137
	v_pk_fma_f32 v[164:165], v[198:199], v[116:117], v[164:165]
	v_cvt_pk_bf16_f32 v124, v124, v125
	v_pk_add_f32 v[164:165], v[120:121], v[164:165]
	v_add_f32_e32 v137, 1.0, v137
	v_rcp_f32_e32 v140, v137
	v_mul_f32_e32 v137, 0x3d122279, v127
	v_fmaak_f32 v137, v127, v137, 0x3f4c422a
	v_mul_f32_e32 v137, v127, v137
	v_mul_f32_e32 v137, 0xc038aa3b, v137
	v_exp_f32_e32 v137, v137
	s_nop 0
	v_add_f32_e32 v137, 1.0, v137
	v_rcp_f32_e32 v141, v137
	s_nop 0
	v_pk_mul_f32 v[126:127], v[126:127], v[140:141]
	s_nop 0
	v_pk_mul_f32 v[126:127], v[164:165], v[126:127]
	s_nop 0
	v_cvt_pk_bf16_f32 v125, v126, v127
	v_lshlrev_b64 v[126:127], 12, v[122:123]
	v_lshl_add_u64 v[126:127], s[70:71], 0, v[126:127]
	v_lshl_add_u64 v[126:127], v[180:181], 1, v[126:127]
	global_store_dwordx2 v[126:127], v[124:125], off
;     __device__ __forceinline__ void operator()(f32x4 (&acc)[2][2][4][2], const Unit& u, int wr, int wc, int fr, int fq) const {
;     ...
;                     for (int n = 0; n < 2; ++n) acc[ai][bj][m][n] = acc[ai][bj][m][n] * rs[4 * ai + m]; }
;         unsigned vmask = 0, smask = 0, emask = 0;
; #pragma unroll
;         for (int j = 0; j < 8; ++j) { const int t = t0 + j, loc = fr * 8 + j;
;             if (loc >= 1 && loc <= 126 && t < M_TOK) vmask |= 1u << j;
;             const int sm = (t < NPROMPT) ? (SEQ_P - 1) : (SEQ_S - 1);
;             if ((t & sm) == 0) smask |= 1u << j;
;             if ((t & sm) == sm) emask |= 1u << j; }
; #pragma unroll
;         for (int n = 0; n < 2; ++n) {
;             const int cg_ = 128 * u.pn + 32 * wc + 8 * fq + 4 * n;
;             const f32x4 w0g = *(const f32x4*)(cw + cg_), w1g = *(const f32x4*)(cw + 4096 + cg_), w2g = *(const f32x4*)(cw + 8192 + cg_), bg = *(const f32x4*)(cb + cg_);
;             const f32x4 w0v = *(const f32x4*)(cw + 2048 + cg_), w1v = *(const f32x4*)(cw + 4096 + 2048 + cg_), w2v = *(const f32x4*)(cw + 8192 + 2048 + cg_), bv = *(const f32x4*)(cb + 2048 + cg_);
;             float h[8][4];
; #pragma unroll
;             for (int i = 0; i < 4; ++i) {
;                 float ag[8], av[8];
; #pragma unroll
;                 for (int j = 0; j < 8; ++j) { ag[j] = acc[j >> 2][0][j & 3][n][i]; av[j] = acc[j >> 2][1][j & 3][n][i]; }
;                 const float lg = dpp_shr1(ag[7]), rg = dpp_shl1(ag[0]), lv = dpp_shr1(av[7]), rv = dpp_shl1(av[0]);
; #pragma unroll
;                 for (int j = 0; j < 8; ++j) {
;                     float Lg = j == 0 ? lg : ag[j == 0 ? 0 : j - 1], Rg = j == 7 ? rg : ag[j == 7 ? 7 : j + 1];
;                     float Lv = j == 0 ? lv : av[j == 0 ? 0 : j - 1], Rv = j == 7 ? rv : av[j == 7 ? 7 : j + 1];
;                     if ((smask >> j) & 1u) { Lg = 0.f; Lv = 0.f; }
;                     if ((emask >> j) & 1u) { Rg = 0.f; Rv = 0.f; }
;                     const float cgv = w0g[i] * Lg + w1g[i] * ag[j] + w2g[i] * Rg + bg[i];
;                     const float cvv = w0v[i] * Lv + w1v[i] * av[j] + w2v[i] * Rv + bv[i];
;                     h[j][i] = gelu_t(cgv) * cvv;
;                 }
;             }
; #pragma unroll
;             for (int j = 0; j < 8; ++j) if ((vmask >> j) & 1u) { u32x2 w; w.x = cvt_pk_bf16(h[j][0], h[j][1]); w.y = cvt_pk_bf16(h[j][2], h[j][3]);
.LBB0_126:
	s_or_b64 exec, exec, s[0:1]
	s_waitcnt lgkmcnt(0)
	v_add_f32_e32 v124, v239, v240
	v_fmamk_f32 v124, v124, 0x3a800000, v218
	s_mov_b32 s0, 0x17ffd
	v_rsq_f32_e32 v140, v124
	v_cmp_gt_i32_e64 s[60:61], s0, v182
	s_movk_i32 s0, 0x7ffd
	v_cmp_gt_i32_e64 s[0:1], s0, v182
	v_add_u32_e32 v124, 3, v182
	v_pk_mul_f32 v[88:89], v[88:89], v[140:141] op_sel_hi:[1,0]
	v_cndmask_b32_e64 v125, v217, v226, s[0:1]
	v_and_b32_e32 v125, v125, v124
	v_pk_mul_f32 v[86:87], v[86:87], v[140:141] op_sel_hi:[1,0]
	v_pk_mul_f32 v[84:85], v[84:85], v[140:141] op_sel_hi:[1,0]
	v_pk_mul_f32 v[82:83], v[82:83], v[140:141] op_sel_hi:[1,0]
	v_cmp_eq_u32_e64 s[46:47], 0, v125
	v_ashrrev_i32_e32 v125, 31, v124
	s_and_saveexec_b64 s[0:1], s[60:61]
	s_cbranch_execz .LBB0_128
	v_cndmask_b32_e64 v127, v205, 0, s[46:47]
	v_cndmask_b32_e64 v126, v204, 0, s[46:47]
	v_pk_mul_f32 v[164:165], v[202:203], v[110:111]
	v_cndmask_b32_e64 v143, v143, 0, s[46:47]
	v_pk_fma_f32 v[126:127], v[126:127], v[98:99], v[164:165]
	v_cndmask_b32_e64 v142, v142, 0, s[46:47]
	v_pk_fma_f32 v[126:127], v[86:87], v[102:103], v[126:127]
	v_cndmask_b32_e64 v199, v201, 0, s[46:47]
	v_pk_add_f32 v[126:127], v[106:107], v[126:127]
	v_cndmask_b32_e64 v198, v200, 0, s[46:47]
	v_mul_f32_e32 v137, 0x3d122279, v126
	v_fmaak_f32 v137, v126, v137, 0x3f4c422a
	v_mul_f32_e32 v137, v126, v137
	v_mul_f32_e32 v137, 0xc038aa3b, v137
	v_exp_f32_e32 v137, v137
	v_pk_mul_f32 v[200:201], v[144:145], v[94:95]
	v_cndmask_b32_e64 v133, v133, 0, s[46:47]
	v_pk_fma_f32 v[198:199], v[198:199], v[90:91], v[200:201]
	v_add_f32_e32 v137, 1.0, v137
	v_rcp_f32_e32 v164, v137
	v_mul_f32_e32 v137, 0x3d122279, v127
	v_fmaak_f32 v137, v127, v137, 0x3f4c422a
	v_mul_f32_e32 v137, v127, v137
	v_mul_f32_e32 v137, 0xc038aa3b, v137
	v_exp_f32_e32 v137, v137
	v_pk_fma_f32 v[198:199], v[82:83], v[114:115], v[198:199]
	v_cndmask_b32_e64 v132, v132, 0, s[46:47]
	v_pk_add_f32 v[198:199], v[118:119], v[198:199]
	v_add_f32_e32 v137, 1.0, v137
	v_rcp_f32_e32 v165, v137
	s_nop 0
	v_pk_mul_f32 v[126:127], v[126:127], v[164:165]
	v_pk_mul_f32 v[164:165], v[134:135], v[112:113]
	v_pk_mul_f32 v[126:127], v[198:199], v[126:127]
	v_pk_fma_f32 v[142:143], v[142:143], v[100:101], v[164:165]
	v_pk_mul_f32 v[198:199], v[128:129], v[96:97]
	v_pk_fma_f32 v[142:143], v[88:89], v[104:105], v[142:143]
	v_pk_fma_f32 v[132:133], v[132:133], v[92:93], v[198:199]
	v_pk_add_f32 v[142:143], v[108:109], v[142:143]
	v_pk_fma_f32 v[132:133], v[84:85], v[116:117], v[132:133]
	v_mul_f32_e32 v137, 0x3d122279, v142
	v_fmaak_f32 v137, v142, v137, 0x3f4c422a
	v_mul_f32_e32 v137, v142, v137
	v_mul_f32_e32 v137, 0xc038aa3b, v137
	v_exp_f32_e32 v137, v137
	v_pk_add_f32 v[132:133], v[120:121], v[132:133]
	v_cvt_pk_bf16_f32 v126, v126, v127
	v_add_f32_e32 v137, 1.0, v137
	v_rcp_f32_e32 v164, v137
	v_mul_f32_e32 v137, 0x3d122279, v143
	v_fmaak_f32 v137, v143, v137, 0x3f4c422a
	v_mul_f32_e32 v137, v143, v137
	v_mul_f32_e32 v137, 0xc038aa3b, v137
	v_exp_f32_e32 v137, v137
	s_nop 0
	v_add_f32_e32 v137, 1.0, v137
	v_rcp_f32_e32 v165, v137
	s_nop 0
	v_pk_mul_f32 v[142:143], v[142:143], v[164:165]
	s_nop 0
	v_pk_mul_f32 v[132:133], v[132:133], v[142:143]
	s_nop 0
	v_cvt_pk_bf16_f32 v127, v132, v133
	v_lshlrev_b64 v[132:133], 12, v[124:125]
	v_lshl_add_u64 v[132:133], s[70:71], 0, v[132:133]
	v_lshl_add_u64 v[132:133], v[180:181], 1, v[132:133]
	global_store_dwordx2 v[132:133], v[126:127], off
.LBB0_128:
	s_or_b64 exec, exec, s[0:1]
	v_add_f32_e32 v126, v189, v197
	v_fmamk_f32 v126, v126, 0x3a800000, v218
	s_mov_b32 s0, 0x17ffc
	v_rsq_f32_e32 v142, v126
	v_cmp_gt_i32_e64 s[62:63], s0, v182
	s_movk_i32 s0, 0x7ffc
	v_cmp_gt_i32_e64 s[0:1], s0, v182
	v_add_u32_e32 v126, 4, v182
	v_pk_mul_f32 v[80:81], v[80:81], v[142:143] op_sel_hi:[1,0]
	v_cndmask_b32_e64 v127, v223, v227, s[0:1]
	v_or_b32_e32 v127, v127, v126
	v_pk_mul_f32 v[78:79], v[78:79], v[142:143] op_sel_hi:[1,0]
	v_pk_mul_f32 v[76:77], v[76:77], v[142:143] op_sel_hi:[1,0]
	v_pk_mul_f32 v[74:75], v[74:75], v[142:143] op_sel_hi:[1,0]
	v_cmp_eq_u32_e64 s[48:49], -1, v127
	v_ashrrev_i32_e32 v127, 31, v126
	s_and_saveexec_b64 s[0:1], s[62:63]
	s_cbranch_execz .LBB0_130
	v_pk_mul_f32 v[164:165], v[86:87], v[110:111]
	v_cndmask_b32_e64 v133, v79, 0, s[48:49]
	v_cndmask_b32_e64 v132, v78, 0, s[48:49]
	v_pk_fma_f32 v[164:165], v[202:203], v[98:99], v[164:165]
	v_pk_mul_f32 v[200:201], v[82:83], v[94:95]
	v_pk_fma_f32 v[132:133], v[102:103], v[132:133], v[164:165]
	v_cndmask_b32_e64 v199, v75, 0, s[48:49]
	v_pk_add_f32 v[132:133], v[106:107], v[132:133]
	v_cndmask_b32_e64 v198, v74, 0, s[48:49]
	v_mul_f32_e32 v137, 0x3d122279, v132
	v_fmaak_f32 v137, v132, v137, 0x3f4c422a
	v_mul_f32_e32 v137, v132, v137
	v_mul_f32_e32 v137, 0xc038aa3b, v137
	v_exp_f32_e32 v137, v137
	v_pk_fma_f32 v[144:145], v[144:145], v[90:91], v[200:201]
	v_add_f32_e32 v137, 1.0, v137
	v_rcp_f32_e32 v164, v137
	v_mul_f32_e32 v137, 0x3d122279, v133
	v_fmaak_f32 v137, v133, v137, 0x3f4c422a
	v_mul_f32_e32 v137, v133, v137
	v_mul_f32_e32 v137, 0xc038aa3b, v137
	v_exp_f32_e32 v137, v137
	v_pk_fma_f32 v[144:145], v[198:199], v[114:115], v[144:145]
	v_pk_mul_f32 v[198:199], v[84:85], v[96:97]
	v_pk_add_f32 v[144:145], v[118:119], v[144:145]
	v_add_f32_e32 v137, 1.0, v137
	v_rcp_f32_e32 v165, v137
	v_pk_fma_f32 v[128:129], v[128:129], v[92:93], v[198:199]
	v_pk_mul_f32 v[132:133], v[132:133], v[164:165]
	v_pk_mul_f32 v[164:165], v[88:89], v[112:113]
	v_pk_mul_f32 v[132:133], v[144:145], v[132:133]
	v_cndmask_b32_e64 v145, v81, 0, s[48:49]
	v_cndmask_b32_e64 v144, v80, 0, s[48:49]
	v_pk_fma_f32 v[134:135], v[134:135], v[100:101], v[164:165]
	v_cndmask_b32_e64 v165, v77, 0, s[48:49]
	v_pk_fma_f32 v[134:135], v[104:105], v[144:145], v[134:135]
	v_cndmask_b32_e64 v164, v76, 0, s[48:49]
	v_pk_add_f32 v[134:135], v[108:109], v[134:135]
	v_pk_fma_f32 v[128:129], v[164:165], v[116:117], v[128:129]
	v_mul_f32_e32 v137, 0x3d122279, v134
	v_fmaak_f32 v137, v134, v137, 0x3f4c422a
	v_mul_f32_e32 v137, v134, v137
	v_mul_f32_e32 v137, 0xc038aa3b, v137
	v_exp_f32_e32 v137, v137
	v_pk_add_f32 v[128:129], v[120:121], v[128:129]
	v_cvt_pk_bf16_f32 v132, v132, v133
	v_add_f32_e32 v137, 1.0, v137
	v_rcp_f32_e32 v144, v137
	v_mul_f32_e32 v137, 0x3d122279, v135
	v_fmaak_f32 v137, v135, v137, 0x3f4c422a
	v_mul_f32_e32 v137, v135, v137
	v_mul_f32_e32 v137, 0xc038aa3b, v137
	v_exp_f32_e32 v137, v137
	s_nop 0
	v_add_f32_e32 v137, 1.0, v137
	v_rcp_f32_e32 v145, v137
	s_nop 0
	v_pk_mul_f32 v[134:135], v[134:135], v[144:145]
	s_nop 0
	v_pk_mul_f32 v[128:129], v[128:129], v[134:135]
	s_nop 0
	v_cvt_pk_bf16_f32 v133, v128, v129
	v_lshlrev_b64 v[128:129], 12, v[126:127]
	v_lshl_add_u64 v[128:129], s[70:71], 0, v[128:129]
	v_lshl_add_u64 v[128:129], v[180:181], 1, v[128:129]
	global_store_dwordx2 v[128:129], v[132:133], off
;     __device__ __forceinline__ void operator()(f32x4 (&acc)[2][2][4][2], const Unit& u, int wr, int wc, int fr, int fq) const {
;     ...
;                     for (int n = 0; n < 2; ++n) acc[ai][bj][m][n] = acc[ai][bj][m][n] * rs[4 * ai + m]; }
;         unsigned vmask = 0, smask = 0, emask = 0;
; #pragma unroll
;         for (int j = 0; j < 8; ++j) { const int t = t0 + j, loc = fr * 8 + j;
;             if (loc >= 1 && loc <= 126 && t < M_TOK) vmask |= 1u << j;
;             const int sm = (t < NPROMPT) ? (SEQ_P - 1) : (SEQ_S - 1);
;             if ((t & sm) == 0) smask |= 1u << j;
;             if ((t & sm) == sm) emask |= 1u << j; }
; #pragma unroll
;         for (int n = 0; n < 2; ++n) {
;             const int cg_ = 128 * u.pn + 32 * wc + 8 * fq + 4 * n;
;             const f32x4 w0g = *(const f32x4*)(cw + cg_), w1g = *(const f32x4*)(cw + 4096 + cg_), w2g = *(const f32x4*)(cw + 8192 + cg_), bg = *(const f32x4*)(cb + cg_);
;             const f32x4 w0v = *(const f32x4*)(cw + 2048 + cg_), w1v = *(const f32x4*)(cw + 4096 + 2048 + cg_), w2v = *(const f32x4*)(cw + 8192 + 2048 + cg_), bv = *(const f32x4*)(cb + 2048 + cg_);
;             float h[8][4];
; #pragma unroll
;             for (int i = 0; i < 4; ++i) {
;                 float ag[8], av[8];
; #pragma unroll
;                 for (int j = 0; j < 8; ++j) { ag[j] = acc[j >> 2][0][j & 3][n][i]; av[j] = acc[j >> 2][1][j & 3][n][i]; }
;                 const float lg = dpp_shr1(ag[7]), rg = dpp_shl1(ag[0]), lv = dpp_shr1(av[7]), rv = dpp_shl1(av[0]);
; #pragma unroll
;                 for (int j = 0; j < 8; ++j) {
;                     float Lg = j == 0 ? lg : ag[j == 0 ? 0 : j - 1], Rg = j == 7 ? rg : ag[j == 7 ? 7 : j + 1];
;                     float Lv = j == 0 ? lv : av[j == 0 ? 0 : j - 1], Rv = j == 7 ? rv : av[j == 7 ? 7 : j + 1];
;                     if ((smask >> j) & 1u) { Lg = 0.f; Lv = 0.f; }
;                     if ((emask >> j) & 1u) { Rg = 0.f; Rv = 0.f; }
;                     const float cgv = w0g[i] * Lg + w1g[i] * ag[j] + w2g[i] * Rg + bg[i];
;                     const float cvv = w0v[i] * Lv + w1v[i] * av[j] + w2v[i] * Rv + bv[i];
;                     h[j][i] = gelu_t(cgv) * cvv;
;                 }
;             }
; #pragma unroll
;             for (int j = 0; j < 8; ++j) if ((vmask >> j) & 1u) { u32x2 w; w.x = cvt_pk_bf16(h[j][0], h[j][1]); w.y = cvt_pk_bf16(h[j][2], h[j][3]);
.LBB0_130:
	s_or_b64 exec, exec, s[0:1]
	v_add_f32_e32 v0, v0, v163
	v_fmamk_f32 v0, v0, 0x3a800000, v218
	s_mov_b32 s0, 0x17ffb
	v_rsq_f32_e32 v144, v0
	v_cmp_gt_i32_e64 s[64:65], s0, v182
	s_movk_i32 s0, 0x7ffb
	v_cmp_gt_i32_e64 s[0:1], s0, v182
	v_add_u32_e32 v128, 5, v182
	v_pk_mul_f32 v[72:73], v[72:73], v[144:145] op_sel_hi:[1,0]
	v_cndmask_b32_e64 v0, v217, v226, s[0:1]
	v_and_b32_e32 v0, v0, v128
	v_pk_mul_f32 v[70:71], v[70:71], v[144:145] op_sel_hi:[1,0]
	v_pk_mul_f32 v[68:69], v[68:69], v[144:145] op_sel_hi:[1,0]
	v_pk_mul_f32 v[66:67], v[66:67], v[144:145] op_sel_hi:[1,0]
	v_cmp_eq_u32_e64 s[50:51], 0, v0
	v_ashrrev_i32_e32 v129, 31, v128
	s_and_saveexec_b64 s[0:1], s[64:65]
	s_cbranch_execz .LBB0_132
	v_cndmask_b32_e64 v87, v87, 0, s[50:51]
	v_cndmask_b32_e64 v86, v86, 0, s[50:51]
	v_pk_mul_f32 v[132:133], v[110:111], v[78:79]
	v_cndmask_b32_e64 v83, v83, 0, s[50:51]
	v_pk_fma_f32 v[86:87], v[98:99], v[86:87], v[132:133]
	v_cndmask_b32_e64 v82, v82, 0, s[50:51]
	v_pk_fma_f32 v[86:87], v[102:103], v[70:71], v[86:87]
	v_pk_mul_f32 v[134:135], v[74:75], v[94:95]
	v_pk_add_f32 v[86:87], v[106:107], v[86:87]
	v_pk_fma_f32 v[82:83], v[82:83], v[90:91], v[134:135]
	v_mul_f32_e32 v0, 0x3d122279, v86
	v_fmaak_f32 v0, v86, v0, 0x3f4c422a
	v_mul_f32_e32 v0, v86, v0
	v_mul_f32_e32 v0, 0xc038aa3b, v0
	v_exp_f32_e32 v0, v0
	v_pk_fma_f32 v[82:83], v[66:67], v[114:115], v[82:83]
	v_cndmask_b32_e64 v85, v85, 0, s[50:51]
	v_pk_add_f32 v[82:83], v[118:119], v[82:83]
	v_add_f32_e32 v0, 1.0, v0
	v_rcp_f32_e32 v132, v0
	v_mul_f32_e32 v0, 0x3d122279, v87
	v_fmaak_f32 v0, v87, v0, 0x3f4c422a
	v_mul_f32_e32 v0, v87, v0
	v_mul_f32_e32 v0, 0xc038aa3b, v0
	v_exp_f32_e32 v0, v0
	v_cndmask_b32_e64 v84, v84, 0, s[50:51]
	v_add_f32_e32 v0, 1.0, v0
	v_rcp_f32_e32 v133, v0
	s_nop 0
	v_pk_mul_f32 v[86:87], v[86:87], v[132:133]
	s_nop 0
	v_pk_mul_f32 v[82:83], v[82:83], v[86:87]
	v_cndmask_b32_e64 v87, v89, 0, s[50:51]
	v_cndmask_b32_e64 v86, v88, 0, s[50:51]
	v_pk_mul_f32 v[88:89], v[112:113], v[80:81]
	v_pk_mul_f32 v[132:133], v[76:77], v[96:97]
	v_pk_fma_f32 v[86:87], v[100:101], v[86:87], v[88:89]
	v_pk_fma_f32 v[84:85], v[84:85], v[92:93], v[132:133]
	v_pk_fma_f32 v[86:87], v[104:105], v[72:73], v[86:87]
	v_pk_fma_f32 v[84:85], v[68:69], v[116:117], v[84:85]
	v_pk_add_f32 v[86:87], v[108:109], v[86:87]
	v_pk_add_f32 v[84:85], v[120:121], v[84:85]
	v_mul_f32_e32 v0, 0x3d122279, v86
	v_fmaak_f32 v0, v86, v0, 0x3f4c422a
	v_mul_f32_e32 v0, v86, v0
	v_mul_f32_e32 v0, 0xc038aa3b, v0
	v_exp_f32_e32 v0, v0
	v_cvt_pk_bf16_f32 v82, v82, v83
	v_add_f32_e32 v0, 1.0, v0
	v_rcp_f32_e32 v88, v0
	v_mul_f32_e32 v0, 0x3d122279, v87
	v_fmaak_f32 v0, v87, v0, 0x3f4c422a
	v_mul_f32_e32 v0, v87, v0
	v_mul_f32_e32 v0, 0xc038aa3b, v0
	v_exp_f32_e32 v0, v0
	s_nop 0
	v_add_f32_e32 v0, 1.0, v0
	v_rcp_f32_e32 v89, v0
	s_nop 0
	v_pk_mul_f32 v[86:87], v[86:87], v[88:89]
	s_nop 0
	v_pk_mul_f32 v[84:85], v[84:85], v[86:87]
	s_nop 0
	v_cvt_pk_bf16_f32 v83, v84, v85
	v_lshlrev_b64 v[84:85], 12, v[128:129]
	v_lshl_add_u64 v[84:85], s[70:71], 0, v[84:85]
	v_lshl_add_u64 v[84:85], v[180:181], 1, v[84:85]
	global_store_dwordx2 v[84:85], v[82:83], off
.LBB0_132:
	s_or_b64 exec, exec, s[0:1]
	s_mov_b32 s0, 0x17ffa
	v_cmp_gt_i32_e64 s[66:67], s0, v182
	s_movk_i32 s0, 0x7ffa
	v_cmp_gt_i32_e64 s[0:1], s0, v182
	v_add_u32_e32 v132, 6, v182
	v_ashrrev_i32_e32 v133, 31, v132
	v_cndmask_b32_e64 v0, v223, v227, s[0:1]
	v_or_b32_e32 v0, v0, v132
	v_cmp_eq_u32_e64 s[52:53], -1, v0
	s_and_saveexec_b64 s[0:1], s[66:67]
	s_cbranch_execz .LBB0_134
	v_pk_mul_f32 v[84:85], v[110:111], v[70:71]
	v_cndmask_b32_e64 v83, v159, 0, s[52:53]
	v_cndmask_b32_e64 v82, v158, 0, s[52:53]
	v_pk_fma_f32 v[78:79], v[98:99], v[78:79], v[84:85]
	v_pk_mul_f32 v[86:87], v[94:95], v[66:67]
	v_pk_fma_f32 v[78:79], v[102:103], v[82:83], v[78:79]
	v_cndmask_b32_e64 v85, v153, 0, s[52:53]
	v_pk_add_f32 v[78:79], v[106:107], v[78:79]
	v_cndmask_b32_e64 v84, v152, 0, s[52:53]
	v_mul_f32_e32 v0, 0x3d122279, v78
	v_fmaak_f32 v0, v78, v0, 0x3f4c422a
	v_mul_f32_e32 v0, v78, v0
	v_mul_f32_e32 v0, 0xc038aa3b, v0
	v_exp_f32_e32 v0, v0
	v_pk_fma_f32 v[74:75], v[74:75], v[90:91], v[86:87]
	v_add_f32_e32 v0, 1.0, v0
	v_rcp_f32_e32 v82, v0
	v_mul_f32_e32 v0, 0x3d122279, v79
	v_fmaak_f32 v0, v79, v0, 0x3f4c422a
	v_mul_f32_e32 v0, v79, v0
	v_mul_f32_e32 v0, 0xc038aa3b, v0
	v_exp_f32_e32 v0, v0
	v_pk_fma_f32 v[74:75], v[114:115], v[84:85], v[74:75]
	v_pk_mul_f32 v[84:85], v[96:97], v[68:69]
	v_pk_add_f32 v[74:75], v[118:119], v[74:75]
	v_add_f32_e32 v0, 1.0, v0
	v_rcp_f32_e32 v83, v0
	v_pk_fma_f32 v[76:77], v[76:77], v[92:93], v[84:85]
	v_pk_mul_f32 v[78:79], v[78:79], v[82:83]
	v_pk_mul_f32 v[82:83], v[112:113], v[72:73]
	v_pk_mul_f32 v[74:75], v[74:75], v[78:79]
	v_cndmask_b32_e64 v79, v149, 0, s[52:53]
	v_cndmask_b32_e64 v78, v148, 0, s[52:53]
	v_pk_fma_f32 v[80:81], v[100:101], v[80:81], v[82:83]
	v_cndmask_b32_e64 v83, v147, 0, s[52:53]
	v_pk_fma_f32 v[78:79], v[104:105], v[78:79], v[80:81]
	v_cndmask_b32_e64 v82, v146, 0, s[52:53]
	v_pk_add_f32 v[78:79], v[108:109], v[78:79]
	v_pk_fma_f32 v[76:77], v[116:117], v[82:83], v[76:77]
	v_mul_f32_e32 v0, 0x3d122279, v78
	v_fmaak_f32 v0, v78, v0, 0x3f4c422a
	v_mul_f32_e32 v0, v78, v0
	v_mul_f32_e32 v0, 0xc038aa3b, v0
	v_exp_f32_e32 v0, v0
	v_pk_add_f32 v[76:77], v[120:121], v[76:77]
	v_cvt_pk_bf16_f32 v74, v74, v75
	v_add_f32_e32 v0, 1.0, v0
	v_rcp_f32_e32 v80, v0
	v_mul_f32_e32 v0, 0x3d122279, v79
	v_fmaak_f32 v0, v79, v0, 0x3f4c422a
	v_mul_f32_e32 v0, v79, v0
	v_mul_f32_e32 v0, 0xc038aa3b, v0
	v_exp_f32_e32 v0, v0
	s_nop 0
	v_add_f32_e32 v0, 1.0, v0
	v_rcp_f32_e32 v81, v0
	s_nop 0
	v_pk_mul_f32 v[78:79], v[78:79], v[80:81]
	s_nop 0
	v_pk_mul_f32 v[76:77], v[76:77], v[78:79]
	s_nop 0
	v_cvt_pk_bf16_f32 v75, v76, v77
	v_lshlrev_b64 v[76:77], 12, v[132:133]
	v_lshl_add_u64 v[76:77], s[70:71], 0, v[76:77]
	v_lshl_add_u64 v[76:77], v[180:181], 1, v[76:77]
	global_store_dwordx2 v[76:77], v[74:75], off
; __device__ __forceinline__ unsigned cvt_pk_bf16(float lo, float hi) { f32x2 v = {lo, hi}; bf16x2_t_ b = __builtin_convertvector(v, bf16x2_t_); return __builtin_bit_cast(unsigned, b); }
; __device__ __forceinline__ float dpp_shr1(float v) { return __int_as_float(__builtin_amdgcn_update_dpp(0, __float_as_int(v), 0x111, 0xF, 0xF, true)); }
;     __device__ __forceinline__ void operator()(f32x4 (&acc)[2][2][4][2], const Unit& u, int wr, int wc, int fr, int fq) const {
;     ...
;         for (int n = 0; n < 2; ++n) {
;             const int cg_ = 128 * u.pn + 32 * wc + 8 * fq + 4 * n;
;             const f32x4 w0g = *(const f32x4*)(cw + cg_), w1g = *(const f32x4*)(cw + 4096 + cg_), w2g = *(const f32x4*)(cw + 8192 + cg_), bg = *(const f32x4*)(cb + cg_);
;             const f32x4 w0v = *(const f32x4*)(cw + 2048 + cg_), w1v = *(const f32x4*)(cw + 4096 + 2048 + cg_), w2v = *(const f32x4*)(cw + 8192 + 2048 + cg_), bv = *(const f32x4*)(cb + 2048 + cg_);
;             float h[8][4];
; #pragma unroll
;             for (int i = 0; i < 4; ++i) {
;                 float ag[8], av[8];
; #pragma unroll
;                 for (int j = 0; j < 8; ++j) { ag[j] = acc[j >> 2][0][j & 3][n][i]; av[j] = acc[j >> 2][1][j & 3][n][i]; }
;                 const float lg = dpp_shr1(ag[7]), rg = dpp_shl1(ag[0]), lv = dpp_shr1(av[7]), rv = dpp_shl1(av[0]);
; #pragma unroll
;                 for (int j = 0; j < 8; ++j) {
;                     float Lg = j == 0 ? lg : ag[j == 0 ? 0 : j - 1], Rg = j == 7 ? rg : ag[j == 7 ? 7 : j + 1];
;                     float Lv = j == 0 ? lv : av[j == 0 ? 0 : j - 1], Rv = j == 7 ? rv : av[j == 7 ? 7 : j + 1];
;                     if ((smask >> j) & 1u) { Lg = 0.f; Lv = 0.f; }
;                     if ((emask >> j) & 1u) { Rg = 0.f; Rv = 0.f; }
;                     const float cgv = w0g[i] * Lg + w1g[i] * ag[j] + w2g[i] * Rg + bg[i];
;                     const float cvv = w0v[i] * Lv + w1v[i] * av[j] + w2v[i] * Rv + bv[i];
;                     h[j][i] = gelu_t(cgv) * cvv;
;                 }
;             }
; #pragma unroll
;             for (int j = 0; j < 8; ++j) if ((vmask >> j) & 1u) { u32x2 w; w.x = cvt_pk_bf16(h[j][0], h[j][1]); w.y = cvt_pk_bf16(h[j][2], h[j][3]);
;                 *(u32x2*)(H2 + (size_t)(t0 + j) * 2048 + cg_) = w; }
.LBB0_134:
	s_or_b64 exec, exec, s[0:1]
	s_mov_b32 s0, 0x17ff9
	v_readlane_b32 s34, v255, 20
	v_cmp_gt_i32_e64 s[0:1], s0, v182
	v_readlane_b32 s35, v255, 21
	s_and_b64 s[76:77], s[34:35], s[0:1]
	s_movk_i32 s0, 0x7ff9
	v_cmp_gt_i32_e64 s[0:1], s0, v182
	v_add_u32_e32 v134, 7, v182
	v_ashrrev_i32_e32 v135, 31, v134
	v_cndmask_b32_e64 v0, v217, v226, s[0:1]
	v_and_b32_e32 v0, v0, v134
	v_cmp_eq_u32_e64 s[54:55], 0, v0
	s_and_saveexec_b64 s[0:1], s[76:77]
	s_cbranch_execz .LBB0_136
	v_cndmask_b32_e64 v71, v71, 0, s[54:55]
	v_cndmask_b32_e64 v70, v70, 0, s[54:55]
	v_pk_mul_f32 v[74:75], v[110:111], v[158:159]
	v_cndmask_b32_e64 v67, v67, 0, s[54:55]
	v_pk_fma_f32 v[70:71], v[98:99], v[70:71], v[74:75]
	v_cndmask_b32_e64 v66, v66, 0, s[54:55]
	v_pk_fma_f32 v[70:71], v[102:103], v[160:161], v[70:71]
	v_pk_mul_f32 v[76:77], v[94:95], v[152:153]
	v_pk_add_f32 v[70:71], v[106:107], v[70:71]
	v_pk_fma_f32 v[66:67], v[90:91], v[66:67], v[76:77]
	v_mul_f32_e32 v0, 0x3d122279, v70
	v_fmaak_f32 v0, v70, v0, 0x3f4c422a
	v_mul_f32_e32 v0, v70, v0
	v_mul_f32_e32 v0, 0xc038aa3b, v0
	v_exp_f32_e32 v0, v0
	v_cndmask_b32_e64 v73, v73, 0, s[54:55]
	v_cndmask_b32_e64 v72, v72, 0, s[54:55]
	v_pk_mul_f32 v[76:77], v[112:113], v[148:149]
	v_add_f32_e32 v0, 1.0, v0
	v_rcp_f32_e32 v74, v0
	v_mul_f32_e32 v0, 0x3d122279, v71
	v_fmaak_f32 v0, v71, v0, 0x3f4c422a
	v_mul_f32_e32 v0, v71, v0
	v_mul_f32_e32 v0, 0xc038aa3b, v0
	v_exp_f32_e32 v0, v0
	v_pk_fma_f32 v[72:73], v[100:101], v[72:73], v[76:77]
	v_pk_fma_f32 v[66:67], v[114:115], v[154:155], v[66:67]
	v_pk_fma_f32 v[72:73], v[104:105], v[156:157], v[72:73]
	v_add_f32_e32 v0, 1.0, v0
	v_pk_add_f32 v[72:73], v[108:109], v[72:73]
	v_rcp_f32_e32 v75, v0
	v_mul_f32_e32 v0, 0x3d122279, v72
	v_fmaak_f32 v0, v72, v0, 0x3f4c422a
	v_mul_f32_e32 v0, v72, v0
	v_mul_f32_e32 v0, 0xc038aa3b, v0
	v_exp_f32_e32 v0, v0
	v_pk_add_f32 v[66:67], v[118:119], v[66:67]
	v_pk_mul_f32 v[70:71], v[70:71], v[74:75]
	v_cndmask_b32_e64 v69, v69, 0, s[54:55]
	v_add_f32_e32 v0, 1.0, v0
	v_pk_mul_f32 v[66:67], v[66:67], v[70:71]
	v_rcp_f32_e32 v70, v0
	v_mul_f32_e32 v0, 0x3d122279, v73
	v_fmaak_f32 v0, v73, v0, 0x3f4c422a
	v_mul_f32_e32 v0, v73, v0
	v_mul_f32_e32 v0, 0xc038aa3b, v0
	v_exp_f32_e32 v0, v0
	v_cndmask_b32_e64 v68, v68, 0, s[54:55]
	v_pk_mul_f32 v[74:75], v[96:97], v[146:147]
	v_cvt_pk_bf16_f32 v66, v66, v67
	v_add_f32_e32 v0, 1.0, v0
	v_rcp_f32_e32 v71, v0
	v_pk_fma_f32 v[68:69], v[92:93], v[68:69], v[74:75]
	v_pk_mul_f32 v[70:71], v[72:73], v[70:71]
	v_pk_fma_f32 v[68:69], v[116:117], v[150:151], v[68:69]
	s_nop 0
	v_pk_add_f32 v[68:69], v[120:121], v[68:69]
	s_nop 0
	v_pk_mul_f32 v[68:69], v[68:69], v[70:71]
	s_nop 0
	v_cvt_pk_bf16_f32 v67, v68, v69
	v_lshlrev_b64 v[68:69], 12, v[134:135]
	v_lshl_add_u64 v[68:69], s[70:71], 0, v[68:69]
	v_lshl_add_u64 v[68:69], v[180:181], 1, v[68:69]
	global_store_dwordx2 v[68:69], v[66:67], off
.LBB0_136:
	s_or_b64 exec, exec, s[0:1]
	v_or_b32_e32 v66, 4, v180
	v_ashrrev_i32_e32 v67, 31, v66
	v_readlane_b32 s0, v255, 4
	v_lshlrev_b64 v[78:79], 2, v[66:67]
	v_readlane_b32 s1, v255, 5
	global_load_dwordx4 v[82:85], v[184:185], off offset:16
	v_mov_b32_e32 v197, v196
	v_lshl_add_u64 v[66:67], s[0:1], 0, v[78:79]
	v_readlane_b32 s0, v255, 6
	v_readlane_b32 s1, v255, 7
	v_mov_b32_e32 v189, v188
	v_mov_b32_e32 v163, v162
	v_lshl_add_u64 v[68:69], s[0:1], 0, v[78:79]
	v_readlane_b32 s0, v255, 8
	v_readlane_b32 s1, v255, 9
	global_load_dwordx4 v[94:97], v[66:67], off
	global_load_dwordx4 v[86:89], v[68:69], off
	global_load_dwordx4 v[90:93], v[186:187], off offset:16
	v_lshl_add_u64 v[66:67], s[0:1], 0, v[78:79]
	v_readlane_b32 s0, v255, 10
	v_readlane_b32 s1, v255, 11
	s_waitcnt vmcnt(11)
	v_mov_b32_e32 v98, v196
	v_mov_b32_e32 v99, v196
	v_lshl_add_u64 v[70:71], s[0:1], 0, v[78:79]
	v_readlane_b32 s0, v255, 14
	v_readlane_b32 s1, v255, 15
	global_load_dwordx4 v[66:69], v[66:67], off
	s_nop 0
	global_load_dwordx4 v[70:73], v[70:71], off
	v_lshl_add_u64 v[74:75], s[0:1], 0, v[78:79]
	v_readlane_b32 s0, v255, 18
	v_readlane_b32 s1, v255, 19
	global_load_dwordx4 v[74:77], v[74:75], off
	s_waitcnt vmcnt(12)
	v_pk_mul_f32 v[104:105], v[62:63], v[196:197]
	v_lshl_add_u64 v[78:79], s[0:1], 0, v[78:79]
	global_load_dwordx4 v[78:81], v[78:79], off
	v_pk_mul_f32 v[102:103], v[54:55], v[196:197]
	v_mov_b32_e32 v54, v188
	v_mov_b32_e32 v55, v188
	v_pk_mul_f32 v[62:63], v[50:51], v[188:189]
	v_mov_b32_e32 v50, v162
	v_mov_b32_e32 v51, v162
	v_pk_mul_f32 v[100:101], v[64:65], v[98:99]
	v_pk_mul_f32 v[98:99], v[56:57], v[98:99]
	v_pk_mul_f32 v[60:61], v[60:61], v[54:55]
	v_pk_mul_f32 v[64:65], v[58:59], v[188:189]
	v_pk_mul_f32 v[58:59], v[52:53], v[54:55]
	v_pk_mul_f32 v[48:49], v[48:49], v[50:51]
	v_pk_mul_f32 v[54:55], v[46:47], v[162:163]
	v_pk_mul_f32 v[44:45], v[44:45], v[50:51]
	v_pk_mul_f32 v[46:47], v[42:43], v[162:163]
	s_waitcnt vmcnt(12)
	v_mov_b32_dpp v108, v54 row_shr:1 row_mask:0xf bank_mask:0xf bound_ctrl:1
	v_mov_b32_dpp v56, v104 row_shl:1 row_mask:0xf bank_mask:0xf bound_ctrl:1
	v_mov_b32_dpp v106, v46 row_shr:1 row_mask:0xf bank_mask:0xf bound_ctrl:1
	v_mov_b32_dpp v50, v102 row_shl:1 row_mask:0xf bank_mask:0xf bound_ctrl:1
	v_mov_b32_dpp v109, v55 row_shr:1 row_mask:0xf bank_mask:0xf bound_ctrl:1
	v_mov_b32_dpp v57, v105 row_shl:1 row_mask:0xf bank_mask:0xf bound_ctrl:1
	v_mov_b32_dpp v107, v47 row_shr:1 row_mask:0xf bank_mask:0xf bound_ctrl:1
	v_mov_b32_dpp v51, v103 row_shl:1 row_mask:0xf bank_mask:0xf bound_ctrl:1
	v_mov_b32_dpp v112, v48 row_shr:1 row_mask:0xf bank_mask:0xf bound_ctrl:1
	v_mov_b32_dpp v52, v100 row_shl:1 row_mask:0xf bank_mask:0xf bound_ctrl:1
	v_mov_b32_dpp v110, v44 row_shr:1 row_mask:0xf bank_mask:0xf bound_ctrl:1
	v_mov_b32_dpp v42, v98 row_shl:1 row_mask:0xf bank_mask:0xf bound_ctrl:1
	v_mov_b32_dpp v113, v49 row_shr:1 row_mask:0xf bank_mask:0xf bound_ctrl:1
	v_mov_b32_dpp v53, v101 row_shl:1 row_mask:0xf bank_mask:0xf bound_ctrl:1
	v_mov_b32_dpp v111, v45 row_shr:1 row_mask:0xf bank_mask:0xf bound_ctrl:1
	v_mov_b32_dpp v43, v99 row_shl:1 row_mask:0xf bank_mask:0xf bound_ctrl:1
	s_waitcnt vmcnt(0)
	s_and_saveexec_b64 s[0:1], s[82:83]
	s_cbranch_execz .LBB0_138
; __device__ __forceinline__ unsigned cvt_pk_bf16(float lo, float hi) { f32x2 v = {lo, hi}; bf16x2_t_ b = __builtin_convertvector(v, bf16x2_t_); return __builtin_bit_cast(unsigned, b); }
; __device__ __forceinline__ float dpp_shr1(float v) { return __int_as_float(__builtin_amdgcn_update_dpp(0, __float_as_int(v), 0x111, 0xF, 0xF, true)); }
;     __device__ __forceinline__ void operator()(f32x4 (&acc)[2][2][4][2], const Unit& u, int wr, int wc, int fr, int fq) const {
;     ...
;         for (int n = 0; n < 2; ++n) {
;             const int cg_ = 128 * u.pn + 32 * wc + 8 * fq + 4 * n;
;             const f32x4 w0g = *(const f32x4*)(cw + cg_), w1g = *(const f32x4*)(cw + 4096 + cg_), w2g = *(const f32x4*)(cw + 8192 + cg_), bg = *(const f32x4*)(cb + cg_);
;             const f32x4 w0v = *(const f32x4*)(cw + 2048 + cg_), w1v = *(const f32x4*)(cw + 4096 + 2048 + cg_), w2v = *(const f32x4*)(cw + 8192 + 2048 + cg_), bv = *(const f32x4*)(cb + 2048 + cg_);
;             float h[8][4];
; #pragma unroll
;             for (int i = 0; i < 4; ++i) {
;                 float ag[8], av[8];
; #pragma unroll
;                 for (int j = 0; j < 8; ++j) { ag[j] = acc[j >> 2][0][j & 3][n][i]; av[j] = acc[j >> 2][1][j & 3][n][i]; }
;                 const float lg = dpp_shr1(ag[7]), rg = dpp_shl1(ag[0]), lv = dpp_shr1(av[7]), rv = dpp_shl1(av[0]);
; #pragma unroll
;                 for (int j = 0; j < 8; ++j) {
;                     float Lg = j == 0 ? lg : ag[j == 0 ? 0 : j - 1], Rg = j == 7 ? rg : ag[j == 7 ? 7 : j + 1];
;                     float Lv = j == 0 ? lv : av[j == 0 ? 0 : j - 1], Rv = j == 7 ? rv : av[j == 7 ? 7 : j + 1];
;                     if ((smask >> j) & 1u) { Lg = 0.f; Lv = 0.f; }
;                     if ((emask >> j) & 1u) { Rg = 0.f; Rv = 0.f; }
;                     const float cgv = w0g[i] * Lg + w1g[i] * ag[j] + w2g[i] * Rg + bg[i];
;                     const float cvv = w0v[i] * Lv + w1v[i] * av[j] + w2v[i] * Rv + bv[i];
;                     h[j][i] = gelu_t(cgv) * cvv;
;                 }
;             }
; #pragma unroll
;             for (int j = 0; j < 8; ++j) if ((vmask >> j) & 1u) { u32x2 w; w.x = cvt_pk_bf16(h[j][0], h[j][1]); w.y = cvt_pk_bf16(h[j][2], h[j][3]);
;                 *(u32x2*)(H2 + (size_t)(t0 + j) * 2048 + cg_) = w; }
	v_pk_mul_f32 v[112:113], v[84:85], v[112:113]
	v_cndmask_b32_e64 v117, v61, 0, s[42:43]
	v_cndmask_b32_e64 v116, v60, 0, s[42:43]
	v_pk_fma_f32 v[112:113], v[100:101], v[96:97], v[112:113]
	v_pk_mul_f32 v[110:111], v[68:69], v[110:111]
	v_pk_fma_f32 v[112:113], v[116:117], v[88:89], v[112:113]
	v_cndmask_b32_e64 v115, v59, 0, s[42:43]
	v_pk_add_f32 v[112:113], v[92:93], v[112:113]
	v_cndmask_b32_e64 v114, v58, 0, s[42:43]
	v_mul_f32_e32 v0, 0x3d122279, v113
	v_fmaak_f32 v0, v113, v0, 0x3f4c422a
	v_mul_f32_e32 v116, 0x3d122279, v112
	v_mul_f32_e32 v0, v113, v0
	v_fmaak_f32 v116, v112, v116, 0x3f4c422a
	v_mul_f32_e32 v0, 0xc038aa3b, v0
	v_mul_f32_e32 v116, v112, v116
	v_exp_f32_e32 v0, v0
	v_mul_f32_e32 v116, 0xc038aa3b, v116
	v_exp_f32_e32 v116, v116
	v_pk_fma_f32 v[110:111], v[98:99], v[72:73], v[110:111]
	v_pk_mul_f32 v[108:109], v[82:83], v[108:109]
	v_pk_fma_f32 v[110:111], v[114:115], v[76:77], v[110:111]
	v_cndmask_b32_e64 v115, v65, 0, s[42:43]
	v_cndmask_b32_e64 v114, v64, 0, s[42:43]
	v_pk_fma_f32 v[108:109], v[104:105], v[94:95], v[108:109]
	v_add_f32_e32 v0, 1.0, v0
	v_pk_fma_f32 v[108:109], v[114:115], v[86:87], v[108:109]
	v_rcp_f32_e32 v117, v0
	v_add_f32_e32 v0, 1.0, v116
	v_pk_add_f32 v[108:109], v[90:91], v[108:109]
	v_rcp_f32_e32 v116, v0
	v_mul_f32_e32 v0, 0x3d122279, v109
	v_fmaak_f32 v0, v109, v0, 0x3f4c422a
	v_mul_f32_e32 v114, 0x3d122279, v108
	v_mul_f32_e32 v0, v109, v0
	v_fmaak_f32 v114, v108, v114, 0x3f4c422a
	v_mul_f32_e32 v0, 0xc038aa3b, v0
	v_mul_f32_e32 v114, v108, v114
	v_exp_f32_e32 v0, v0
	v_mul_f32_e32 v114, 0xc038aa3b, v114
	v_exp_f32_e32 v114, v114
	v_pk_add_f32 v[110:111], v[80:81], v[110:111]
	v_add_f32_e32 v0, 1.0, v0
	v_rcp_f32_e32 v115, v0
	v_add_f32_e32 v0, 1.0, v114
	v_rcp_f32_e32 v114, v0
	v_pk_mul_f32 v[112:113], v[112:113], v[116:117]
	v_pk_mul_f32 v[106:107], v[66:67], v[106:107]
	v_pk_mul_f32 v[110:111], v[110:111], v[112:113]
	v_cndmask_b32_e64 v113, v63, 0, s[42:43]
	v_cndmask_b32_e64 v112, v62, 0, s[42:43]
	v_pk_fma_f32 v[106:107], v[102:103], v[70:71], v[106:107]
	v_pk_mul_f32 v[108:109], v[108:109], v[114:115]
	v_pk_fma_f32 v[106:107], v[112:113], v[74:75], v[106:107]
	s_nop 0
	v_pk_add_f32 v[106:107], v[78:79], v[106:107]
	s_nop 0
	v_pk_mul_f32 v[106:107], v[106:107], v[108:109]
	v_lshlrev_b64 v[108:109], 12, v[182:183]
	v_lshl_add_u64 v[108:109], s[70:71], 0, v[108:109]
	v_cvt_pk_bf16_f32 v106, v106, v107
	v_cvt_pk_bf16_f32 v107, v110, v111
	v_lshl_add_u64 v[108:109], v[180:181], 1, v[108:109]
	global_store_dwordx2 v[108:109], v[106:107], off offset:8
.LBB0_138:
	s_or_b64 exec, exec, s[0:1]
	v_mov_b32_e32 v139, v138
	v_mov_b32_e32 v106, v138
	v_mov_b32_e32 v107, v138
	v_pk_mul_f32 v[40:41], v[40:41], v[106:107]
	v_pk_mul_f32 v[38:39], v[38:39], v[138:139]
	v_pk_mul_f32 v[36:37], v[36:37], v[106:107]
	v_pk_mul_f32 v[34:35], v[34:35], v[138:139]
	s_and_saveexec_b64 s[0:1], s[56:57]
	s_cbranch_execz .LBB0_140
	v_cndmask_b32_e64 v105, v105, 0, vcc
	v_cndmask_b32_e64 v104, v104, 0, vcc
	v_pk_mul_f32 v[106:107], v[64:65], v[94:95]
	v_cndmask_b32_e64 v103, v103, 0, vcc
	v_pk_fma_f32 v[104:105], v[104:105], v[82:83], v[106:107]
	v_cndmask_b32_e64 v102, v102, 0, vcc
	v_pk_fma_f32 v[104:105], v[38:39], v[86:87], v[104:105]
	v_pk_mul_f32 v[108:109], v[62:63], v[70:71]
	v_pk_add_f32 v[104:105], v[90:91], v[104:105]
	v_pk_fma_f32 v[102:103], v[102:103], v[66:67], v[108:109]
	v_mul_f32_e32 v0, 0x3d122279, v104
	v_fmaak_f32 v0, v104, v0, 0x3f4c422a
	v_mul_f32_e32 v0, v104, v0
	v_mul_f32_e32 v0, 0xc038aa3b, v0
	v_exp_f32_e32 v0, v0
	v_pk_fma_f32 v[102:103], v[34:35], v[74:75], v[102:103]
	v_cndmask_b32_e64 v101, v101, 0, vcc
	v_pk_add_f32 v[102:103], v[78:79], v[102:103]
	v_add_f32_e32 v0, 1.0, v0
	v_rcp_f32_e32 v106, v0
	v_mul_f32_e32 v0, 0x3d122279, v105
	v_fmaak_f32 v0, v105, v0, 0x3f4c422a
	v_mul_f32_e32 v0, v105, v0
	v_mul_f32_e32 v0, 0xc038aa3b, v0
	v_exp_f32_e32 v0, v0
	v_cndmask_b32_e64 v100, v100, 0, vcc
	v_cndmask_b32_e64 v99, v99, 0, vcc
	v_cndmask_b32_e64 v98, v98, 0, vcc
	v_add_f32_e32 v0, 1.0, v0
	v_rcp_f32_e32 v107, v0
	s_nop 0
	v_pk_mul_f32 v[104:105], v[104:105], v[106:107]
	s_nop 0
	v_pk_mul_f32 v[102:103], v[102:103], v[104:105]
	v_pk_mul_f32 v[104:105], v[60:61], v[96:97]
	v_pk_mul_f32 v[106:107], v[58:59], v[72:73]
	v_pk_fma_f32 v[100:101], v[100:101], v[84:85], v[104:105]
	v_pk_fma_f32 v[98:99], v[98:99], v[68:69], v[106:107]
	v_pk_fma_f32 v[100:101], v[40:41], v[88:89], v[100:101]
	v_pk_fma_f32 v[98:99], v[36:37], v[76:77], v[98:99]
	v_pk_add_f32 v[100:101], v[92:93], v[100:101]
	v_pk_add_f32 v[98:99], v[80:81], v[98:99]
	v_mul_f32_e32 v0, 0x3d122279, v100
	v_fmaak_f32 v0, v100, v0, 0x3f4c422a
	v_mul_f32_e32 v0, v100, v0
	v_mul_f32_e32 v0, 0xc038aa3b, v0
	v_exp_f32_e32 v0, v0
	s_nop 0
	v_add_f32_e32 v0, 1.0, v0
	v_rcp_f32_e32 v104, v0
	v_mul_f32_e32 v0, 0x3d122279, v101
	v_fmaak_f32 v0, v101, v0, 0x3f4c422a
	v_mul_f32_e32 v0, v101, v0
	v_mul_f32_e32 v0, 0xc038aa3b, v0
	v_exp_f32_e32 v0, v0
	s_nop 0
	v_add_f32_e32 v0, 1.0, v0
	v_rcp_f32_e32 v105, v0
	s_nop 0
	v_pk_mul_f32 v[100:101], v[100:101], v[104:105]
	s_nop 0
	v_pk_mul_f32 v[98:99], v[98:99], v[100:101]
	v_cvt_pk_bf16_f32 v100, v102, v103
	v_cvt_pk_bf16_f32 v101, v98, v99
	v_lshlrev_b64 v[98:99], 12, v[130:131]
	v_lshl_add_u64 v[98:99], s[70:71], 0, v[98:99]
	v_lshl_add_u64 v[98:99], v[180:181], 1, v[98:99]
	global_store_dwordx2 v[98:99], v[100:101], off offset:8
; __device__ __forceinline__ unsigned cvt_pk_bf16(float lo, float hi) { f32x2 v = {lo, hi}; bf16x2_t_ b = __builtin_convertvector(v, bf16x2_t_); return __builtin_bit_cast(unsigned, b); }
; __device__ __forceinline__ float dpp_shr1(float v) { return __int_as_float(__builtin_amdgcn_update_dpp(0, __float_as_int(v), 0x111, 0xF, 0xF, true)); }
;     __device__ __forceinline__ void operator()(f32x4 (&acc)[2][2][4][2], const Unit& u, int wr, int wc, int fr, int fq) const {
;     ...
;         for (int n = 0; n < 2; ++n) {
;             const int cg_ = 128 * u.pn + 32 * wc + 8 * fq + 4 * n;
;             const f32x4 w0g = *(const f32x4*)(cw + cg_), w1g = *(const f32x4*)(cw + 4096 + cg_), w2g = *(const f32x4*)(cw + 8192 + cg_), bg = *(const f32x4*)(cb + cg_);
;             const f32x4 w0v = *(const f32x4*)(cw + 2048 + cg_), w1v = *(const f32x4*)(cw + 4096 + 2048 + cg_), w2v = *(const f32x4*)(cw + 8192 + 2048 + cg_), bv = *(const f32x4*)(cb + 2048 + cg_);
;             float h[8][4];
; #pragma unroll
;             for (int i = 0; i < 4; ++i) {
;                 float ag[8], av[8];
; #pragma unroll
;                 for (int j = 0; j < 8; ++j) { ag[j] = acc[j >> 2][0][j & 3][n][i]; av[j] = acc[j >> 2][1][j & 3][n][i]; }
;                 const float lg = dpp_shr1(ag[7]), rg = dpp_shl1(ag[0]), lv = dpp_shr1(av[7]), rv = dpp_shl1(av[0]);
; #pragma unroll
;                 for (int j = 0; j < 8; ++j) {
;                     float Lg = j == 0 ? lg : ag[j == 0 ? 0 : j - 1], Rg = j == 7 ? rg : ag[j == 7 ? 7 : j + 1];
;                     float Lv = j == 0 ? lv : av[j == 0 ? 0 : j - 1], Rv = j == 7 ? rv : av[j == 7 ? 7 : j + 1];
;                     if ((smask >> j) & 1u) { Lg = 0.f; Lv = 0.f; }
;                     if ((emask >> j) & 1u) { Rg = 0.f; Rv = 0.f; }
;                     const float cgv = w0g[i] * Lg + w1g[i] * ag[j] + w2g[i] * Rg + bg[i];
;                     const float cvv = w0v[i] * Lv + w1v[i] * av[j] + w2v[i] * Rv + bv[i];
;                     h[j][i] = gelu_t(cgv) * cvv;
;                 }
;             }
; #pragma unroll
;             for (int j = 0; j < 8; ++j) if ((vmask >> j) & 1u) { u32x2 w; w.x = cvt_pk_bf16(h[j][0], h[j][1]); w.y = cvt_pk_bf16(h[j][2], h[j][3]);
;                 *(u32x2*)(H2 + (size_t)(t0 + j) * 2048 + cg_) = w; }
.LBB0_140:
	s_or_b64 exec, exec, s[0:1]
	v_mov_b32_e32 v137, v136
	v_mov_b32_e32 v98, v136
	v_mov_b32_e32 v99, v136
	v_pk_mul_f32 v[32:33], v[32:33], v[98:99]
	v_pk_mul_f32 v[30:31], v[30:31], v[136:137]
	v_pk_mul_f32 v[28:29], v[28:29], v[98:99]
	v_pk_mul_f32 v[26:27], v[26:27], v[136:137]
	s_and_saveexec_b64 s[0:1], s[58:59]
	s_cbranch_execz .LBB0_142
	v_pk_mul_f32 v[100:101], v[38:39], v[94:95]
	v_cndmask_b32_e64 v99, v31, 0, s[44:45]
	v_cndmask_b32_e64 v98, v30, 0, s[44:45]
	v_pk_fma_f32 v[64:65], v[64:65], v[82:83], v[100:101]
	v_pk_mul_f32 v[102:103], v[34:35], v[70:71]
	v_pk_fma_f32 v[64:65], v[98:99], v[86:87], v[64:65]
	v_cndmask_b32_e64 v101, v27, 0, s[44:45]
	v_pk_add_f32 v[64:65], v[90:91], v[64:65]
	v_cndmask_b32_e64 v100, v26, 0, s[44:45]
	v_mul_f32_e32 v0, 0x3d122279, v64
	v_fmaak_f32 v0, v64, v0, 0x3f4c422a
	v_mul_f32_e32 v0, v64, v0
	v_mul_f32_e32 v0, 0xc038aa3b, v0
	v_exp_f32_e32 v0, v0
	v_pk_fma_f32 v[62:63], v[62:63], v[66:67], v[102:103]
	v_add_f32_e32 v0, 1.0, v0
	v_rcp_f32_e32 v98, v0
	v_mul_f32_e32 v0, 0x3d122279, v65
	v_fmaak_f32 v0, v65, v0, 0x3f4c422a
	v_mul_f32_e32 v0, v65, v0
	v_mul_f32_e32 v0, 0xc038aa3b, v0
	v_exp_f32_e32 v0, v0
	v_pk_fma_f32 v[62:63], v[100:101], v[74:75], v[62:63]
	v_pk_mul_f32 v[100:101], v[36:37], v[72:73]
	v_pk_add_f32 v[62:63], v[78:79], v[62:63]
	v_add_f32_e32 v0, 1.0, v0
	v_rcp_f32_e32 v99, v0
	v_pk_fma_f32 v[58:59], v[58:59], v[68:69], v[100:101]
	v_pk_mul_f32 v[64:65], v[64:65], v[98:99]
	v_pk_mul_f32 v[98:99], v[40:41], v[96:97]
	v_pk_mul_f32 v[62:63], v[62:63], v[64:65]
	v_cndmask_b32_e64 v65, v33, 0, s[44:45]
	v_cndmask_b32_e64 v64, v32, 0, s[44:45]
	v_pk_fma_f32 v[60:61], v[60:61], v[84:85], v[98:99]
	v_cndmask_b32_e64 v99, v29, 0, s[44:45]
	v_pk_fma_f32 v[60:61], v[64:65], v[88:89], v[60:61]
	v_cndmask_b32_e64 v98, v28, 0, s[44:45]
	v_pk_add_f32 v[60:61], v[92:93], v[60:61]
	v_pk_fma_f32 v[58:59], v[98:99], v[76:77], v[58:59]
	v_mul_f32_e32 v0, 0x3d122279, v60
	v_fmaak_f32 v0, v60, v0, 0x3f4c422a
	v_mul_f32_e32 v0, v60, v0
	v_mul_f32_e32 v0, 0xc038aa3b, v0
	v_exp_f32_e32 v0, v0
	v_pk_add_f32 v[58:59], v[80:81], v[58:59]
	v_add_f32_e32 v0, 1.0, v0
	v_rcp_f32_e32 v64, v0
	v_mul_f32_e32 v0, 0x3d122279, v61
	v_fmaak_f32 v0, v61, v0, 0x3f4c422a
	v_mul_f32_e32 v0, v61, v0
	v_mul_f32_e32 v0, 0xc038aa3b, v0
	v_exp_f32_e32 v0, v0
	s_nop 0
	v_add_f32_e32 v0, 1.0, v0
	v_rcp_f32_e32 v65, v0
	s_nop 0
	v_pk_mul_f32 v[60:61], v[60:61], v[64:65]
	s_nop 0
	v_pk_mul_f32 v[58:59], v[58:59], v[60:61]
	v_cvt_pk_bf16_f32 v60, v62, v63
	v_cvt_pk_bf16_f32 v61, v58, v59
	v_lshlrev_b64 v[58:59], 12, v[122:123]
	v_lshl_add_u64 v[58:59], s[70:71], 0, v[58:59]
	v_lshl_add_u64 v[58:59], v[180:181], 1, v[58:59]
	global_store_dwordx2 v[58:59], v[60:61], off offset:8
; __device__ __forceinline__ unsigned cvt_pk_bf16(float lo, float hi) { f32x2 v = {lo, hi}; bf16x2_t_ b = __builtin_convertvector(v, bf16x2_t_); return __builtin_bit_cast(unsigned, b); }
; __device__ __forceinline__ float dpp_shr1(float v) { return __int_as_float(__builtin_amdgcn_update_dpp(0, __float_as_int(v), 0x111, 0xF, 0xF, true)); }
;     __device__ __forceinline__ void operator()(f32x4 (&acc)[2][2][4][2], const Unit& u, int wr, int wc, int fr, int fq) const {
;     ...
;         for (int n = 0; n < 2; ++n) {
;             const int cg_ = 128 * u.pn + 32 * wc + 8 * fq + 4 * n;
;             const f32x4 w0g = *(const f32x4*)(cw + cg_), w1g = *(const f32x4*)(cw + 4096 + cg_), w2g = *(const f32x4*)(cw + 8192 + cg_), bg = *(const f32x4*)(cb + cg_);
;             const f32x4 w0v = *(const f32x4*)(cw + 2048 + cg_), w1v = *(const f32x4*)(cw + 4096 + 2048 + cg_), w2v = *(const f32x4*)(cw + 8192 + 2048 + cg_), bv = *(const f32x4*)(cb + 2048 + cg_);
;             float h[8][4];
; #pragma unroll
;             for (int i = 0; i < 4; ++i) {
;                 float ag[8], av[8];
; #pragma unroll
;                 for (int j = 0; j < 8; ++j) { ag[j] = acc[j >> 2][0][j & 3][n][i]; av[j] = acc[j >> 2][1][j & 3][n][i]; }
;                 const float lg = dpp_shr1(ag[7]), rg = dpp_shl1(ag[0]), lv = dpp_shr1(av[7]), rv = dpp_shl1(av[0]);
; #pragma unroll
;                 for (int j = 0; j < 8; ++j) {
;                     float Lg = j == 0 ? lg : ag[j == 0 ? 0 : j - 1], Rg = j == 7 ? rg : ag[j == 7 ? 7 : j + 1];
;                     float Lv = j == 0 ? lv : av[j == 0 ? 0 : j - 1], Rv = j == 7 ? rv : av[j == 7 ? 7 : j + 1];
;                     if ((smask >> j) & 1u) { Lg = 0.f; Lv = 0.f; }
;                     if ((emask >> j) & 1u) { Rg = 0.f; Rv = 0.f; }
;                     const float cgv = w0g[i] * Lg + w1g[i] * ag[j] + w2g[i] * Rg + bg[i];
;                     const float cvv = w0v[i] * Lv + w1v[i] * av[j] + w2v[i] * Rv + bv[i];
;                     h[j][i] = gelu_t(cgv) * cvv;
;                 }
;             }
; #pragma unroll
;             for (int j = 0; j < 8; ++j) if ((vmask >> j) & 1u) { u32x2 w; w.x = cvt_pk_bf16(h[j][0], h[j][1]); w.y = cvt_pk_bf16(h[j][2], h[j][3]);
;                 *(u32x2*)(H2 + (size_t)(t0 + j) * 2048 + cg_) = w; }
.LBB0_142:
	s_or_b64 exec, exec, s[0:1]
	v_mov_b32_e32 v141, v140
	v_mov_b32_e32 v58, v140
	v_mov_b32_e32 v59, v140
	v_pk_mul_f32 v[24:25], v[24:25], v[58:59]
	v_pk_mul_f32 v[22:23], v[22:23], v[140:141]
	v_pk_mul_f32 v[20:21], v[20:21], v[58:59]
	v_pk_mul_f32 v[18:19], v[18:19], v[140:141]
	s_and_saveexec_b64 s[0:1], s[60:61]
	s_cbranch_execz .LBB0_144
	v_cndmask_b32_e64 v39, v39, 0, s[46:47]
	v_cndmask_b32_e64 v38, v38, 0, s[46:47]
	v_pk_mul_f32 v[58:59], v[30:31], v[94:95]
	v_cndmask_b32_e64 v35, v35, 0, s[46:47]
	v_pk_fma_f32 v[38:39], v[38:39], v[82:83], v[58:59]
	v_cndmask_b32_e64 v34, v34, 0, s[46:47]
	v_pk_fma_f32 v[38:39], v[22:23], v[86:87], v[38:39]
	v_pk_mul_f32 v[60:61], v[26:27], v[70:71]
	v_pk_add_f32 v[38:39], v[90:91], v[38:39]
	v_pk_fma_f32 v[34:35], v[34:35], v[66:67], v[60:61]
	v_mul_f32_e32 v0, 0x3d122279, v38
	v_fmaak_f32 v0, v38, v0, 0x3f4c422a
	v_mul_f32_e32 v0, v38, v0
	v_mul_f32_e32 v0, 0xc038aa3b, v0
	v_exp_f32_e32 v0, v0
	v_pk_fma_f32 v[34:35], v[18:19], v[74:75], v[34:35]
	v_cndmask_b32_e64 v37, v37, 0, s[46:47]
	v_pk_add_f32 v[34:35], v[78:79], v[34:35]
	v_add_f32_e32 v0, 1.0, v0
	v_rcp_f32_e32 v58, v0
	v_mul_f32_e32 v0, 0x3d122279, v39
	v_fmaak_f32 v0, v39, v0, 0x3f4c422a
	v_mul_f32_e32 v0, v39, v0
	v_mul_f32_e32 v0, 0xc038aa3b, v0
	v_exp_f32_e32 v0, v0
	v_cndmask_b32_e64 v36, v36, 0, s[46:47]
	v_add_f32_e32 v0, 1.0, v0
	v_rcp_f32_e32 v59, v0
	s_nop 0
	v_pk_mul_f32 v[38:39], v[38:39], v[58:59]
	s_nop 0
	v_pk_mul_f32 v[34:35], v[34:35], v[38:39]
	v_cndmask_b32_e64 v39, v41, 0, s[46:47]
	v_cndmask_b32_e64 v38, v40, 0, s[46:47]
	v_pk_mul_f32 v[40:41], v[32:33], v[96:97]
	v_pk_mul_f32 v[58:59], v[28:29], v[72:73]
	v_pk_fma_f32 v[38:39], v[38:39], v[84:85], v[40:41]
	v_pk_fma_f32 v[36:37], v[36:37], v[68:69], v[58:59]
	v_pk_fma_f32 v[38:39], v[24:25], v[88:89], v[38:39]
	v_pk_fma_f32 v[36:37], v[20:21], v[76:77], v[36:37]
	v_pk_add_f32 v[38:39], v[92:93], v[38:39]
	v_pk_add_f32 v[36:37], v[80:81], v[36:37]
	v_mul_f32_e32 v0, 0x3d122279, v38
	v_fmaak_f32 v0, v38, v0, 0x3f4c422a
	v_mul_f32_e32 v0, v38, v0
	v_mul_f32_e32 v0, 0xc038aa3b, v0
	v_exp_f32_e32 v0, v0
	v_cvt_pk_bf16_f32 v34, v34, v35
	v_add_f32_e32 v0, 1.0, v0
	v_rcp_f32_e32 v40, v0
	v_mul_f32_e32 v0, 0x3d122279, v39
	v_fmaak_f32 v0, v39, v0, 0x3f4c422a
	v_mul_f32_e32 v0, v39, v0
	v_mul_f32_e32 v0, 0xc038aa3b, v0
	v_exp_f32_e32 v0, v0
	s_nop 0
	v_add_f32_e32 v0, 1.0, v0
	v_rcp_f32_e32 v41, v0
	s_nop 0
	v_pk_mul_f32 v[38:39], v[38:39], v[40:41]
	s_nop 0
	v_pk_mul_f32 v[36:37], v[36:37], v[38:39]
	s_nop 0
	v_cvt_pk_bf16_f32 v35, v36, v37
	v_lshlrev_b64 v[36:37], 12, v[124:125]
	v_lshl_add_u64 v[36:37], s[70:71], 0, v[36:37]
	v_lshl_add_u64 v[36:37], v[180:181], 1, v[36:37]
	global_store_dwordx2 v[36:37], v[34:35], off offset:8
.LBB0_144:
	s_or_b64 exec, exec, s[0:1]
	v_mov_b32_e32 v143, v142
	v_mov_b32_e32 v34, v142
	v_mov_b32_e32 v35, v142
	v_pk_mul_f32 v[16:17], v[16:17], v[34:35]
	v_pk_mul_f32 v[14:15], v[14:15], v[142:143]
	v_pk_mul_f32 v[12:13], v[12:13], v[34:35]
	v_pk_mul_f32 v[10:11], v[10:11], v[142:143]
	s_and_saveexec_b64 s[0:1], s[62:63]
	s_cbranch_execz .LBB0_146
	v_pk_mul_f32 v[36:37], v[22:23], v[94:95]
	v_cndmask_b32_e64 v35, v15, 0, s[48:49]
	v_cndmask_b32_e64 v34, v14, 0, s[48:49]
	v_pk_fma_f32 v[30:31], v[30:31], v[82:83], v[36:37]
	v_pk_mul_f32 v[38:39], v[18:19], v[70:71]
	v_pk_fma_f32 v[30:31], v[34:35], v[86:87], v[30:31]
	v_cndmask_b32_e64 v37, v11, 0, s[48:49]
	v_pk_add_f32 v[30:31], v[90:91], v[30:31]
	v_cndmask_b32_e64 v36, v10, 0, s[48:49]
	v_mul_f32_e32 v0, 0x3d122279, v30
	v_fmaak_f32 v0, v30, v0, 0x3f4c422a
	v_mul_f32_e32 v0, v30, v0
	v_mul_f32_e32 v0, 0xc038aa3b, v0
	v_exp_f32_e32 v0, v0
	v_pk_fma_f32 v[26:27], v[26:27], v[66:67], v[38:39]
	v_add_f32_e32 v0, 1.0, v0
	v_rcp_f32_e32 v34, v0
	v_mul_f32_e32 v0, 0x3d122279, v31
	v_fmaak_f32 v0, v31, v0, 0x3f4c422a
	v_mul_f32_e32 v0, v31, v0
	v_mul_f32_e32 v0, 0xc038aa3b, v0
	v_exp_f32_e32 v0, v0
	v_pk_fma_f32 v[26:27], v[36:37], v[74:75], v[26:27]
	v_pk_mul_f32 v[36:37], v[20:21], v[72:73]
	v_pk_add_f32 v[26:27], v[78:79], v[26:27]
	v_add_f32_e32 v0, 1.0, v0
	v_rcp_f32_e32 v35, v0
	v_pk_fma_f32 v[28:29], v[28:29], v[68:69], v[36:37]
	v_pk_mul_f32 v[30:31], v[30:31], v[34:35]
	v_pk_mul_f32 v[34:35], v[24:25], v[96:97]
	v_pk_mul_f32 v[26:27], v[26:27], v[30:31]
	v_cndmask_b32_e64 v31, v17, 0, s[48:49]
	v_cndmask_b32_e64 v30, v16, 0, s[48:49]
	v_pk_fma_f32 v[32:33], v[32:33], v[84:85], v[34:35]
	v_cndmask_b32_e64 v35, v13, 0, s[48:49]
	v_pk_fma_f32 v[30:31], v[30:31], v[88:89], v[32:33]
	v_cndmask_b32_e64 v34, v12, 0, s[48:49]
	v_pk_add_f32 v[30:31], v[92:93], v[30:31]
	v_pk_fma_f32 v[28:29], v[34:35], v[76:77], v[28:29]
	v_mul_f32_e32 v0, 0x3d122279, v30
	v_fmaak_f32 v0, v30, v0, 0x3f4c422a
	v_mul_f32_e32 v0, v30, v0
	v_mul_f32_e32 v0, 0xc038aa3b, v0
	v_exp_f32_e32 v0, v0
	v_pk_add_f32 v[28:29], v[80:81], v[28:29]
	v_cvt_pk_bf16_f32 v26, v26, v27
	v_add_f32_e32 v0, 1.0, v0
	v_rcp_f32_e32 v32, v0
	v_mul_f32_e32 v0, 0x3d122279, v31
	v_fmaak_f32 v0, v31, v0, 0x3f4c422a
	v_mul_f32_e32 v0, v31, v0
	v_mul_f32_e32 v0, 0xc038aa3b, v0
	v_exp_f32_e32 v0, v0
	s_nop 0
	v_add_f32_e32 v0, 1.0, v0
	v_rcp_f32_e32 v33, v0
	s_nop 0
	v_pk_mul_f32 v[30:31], v[30:31], v[32:33]
	s_nop 0
	v_pk_mul_f32 v[28:29], v[28:29], v[30:31]
	s_nop 0
	v_cvt_pk_bf16_f32 v27, v28, v29
	v_lshlrev_b64 v[28:29], 12, v[126:127]
	v_lshl_add_u64 v[28:29], s[70:71], 0, v[28:29]
	v_lshl_add_u64 v[28:29], v[180:181], 1, v[28:29]
	global_store_dwordx2 v[28:29], v[26:27], off offset:8

; __device__ __forceinline__ unsigned cvt_pk_bf16(float lo, float hi) { f32x2 v = {lo, hi}; bf16x2_t_ b = __builtin_convertvector(v, bf16x2_t_); return __builtin_bit_cast(unsigned, b); }
;     __device__ __forceinline__ void operator()(f32x4 (&acc)[2][2][4][2], const Unit& u, int wr, int wc, int fr, int fq) const {
;     ...
;                 for (int j = 0; j < 8; ++j) {
;                     float Lg = j == 0 ? lg : ag[j == 0 ? 0 : j - 1], Rg = j == 7 ? rg : ag[j == 7 ? 7 : j + 1];
;                     float Lv = j == 0 ? lv : av[j == 0 ? 0 : j - 1], Rv = j == 7 ? rv : av[j == 7 ? 7 : j + 1];
;                     if ((smask >> j) & 1u) { Lg = 0.f; Lv = 0.f; }
;                     if ((emask >> j) & 1u) { Rg = 0.f; Rv = 0.f; }
;                     const float cgv = w0g[i] * Lg + w1g[i] * ag[j] + w2g[i] * Rg + bg[i];
;                     const float cvv = w0v[i] * Lv + w1v[i] * av[j] + w2v[i] * Rv + bv[i];
;                     h[j][i] = gelu_t(cgv) * cvv;
;                 }
;             }
; #pragma unroll
;             for (int j = 0; j < 8; ++j) if ((vmask >> j) & 1u) { u32x2 w; w.x = cvt_pk_bf16(h[j][0], h[j][1]); w.y = cvt_pk_bf16(h[j][2], h[j][3]);
;                 *(u32x2*)(H2 + (size_t)(t0 + j) * 2048 + cg_) = w; }
.LBB0_149:
	v_cndmask_b32_e64 v7, v7, 0, s[54:55]
	v_cndmask_b32_e64 v6, v6, 0, s[54:55]
	v_pk_mul_f32 v[10:11], v[54:55], v[94:95]
	v_cndmask_b32_e64 v3, v3, 0, s[54:55]
	v_pk_fma_f32 v[6:7], v[6:7], v[82:83], v[10:11]
	v_cndmask_b32_e64 v2, v2, 0, s[54:55]
	v_pk_fma_f32 v[6:7], v[86:87], v[56:57], v[6:7]
	v_pk_mul_f32 v[12:13], v[46:47], v[70:71]
	v_pk_add_f32 v[6:7], v[90:91], v[6:7]
	v_pk_fma_f32 v[2:3], v[2:3], v[66:67], v[12:13]
	v_mul_f32_e32 v0, 0x3d122279, v6
	v_fmaak_f32 v0, v6, v0, 0x3f4c422a
	v_mul_f32_e32 v0, v6, v0
	v_mul_f32_e32 v0, 0xc038aa3b, v0
	v_exp_f32_e32 v0, v0
	v_cndmask_b32_e64 v9, v9, 0, s[54:55]
	v_cndmask_b32_e64 v8, v8, 0, s[54:55]
	v_pk_mul_f32 v[12:13], v[48:49], v[96:97]
	v_add_f32_e32 v0, 1.0, v0
	v_rcp_f32_e32 v10, v0
	v_mul_f32_e32 v0, 0x3d122279, v7
	v_fmaak_f32 v0, v7, v0, 0x3f4c422a
	v_mul_f32_e32 v0, v7, v0
	v_mul_f32_e32 v0, 0xc038aa3b, v0
	v_exp_f32_e32 v0, v0
	v_pk_fma_f32 v[8:9], v[8:9], v[84:85], v[12:13]
	v_pk_fma_f32 v[2:3], v[74:75], v[50:51], v[2:3]
	v_pk_fma_f32 v[8:9], v[88:89], v[52:53], v[8:9]
	v_add_f32_e32 v0, 1.0, v0
	v_pk_add_f32 v[8:9], v[92:93], v[8:9]
	v_rcp_f32_e32 v11, v0
	v_mul_f32_e32 v0, 0x3d122279, v8
	v_fmaak_f32 v0, v8, v0, 0x3f4c422a
	v_mul_f32_e32 v0, v8, v0
	v_mul_f32_e32 v0, 0xc038aa3b, v0
	v_exp_f32_e32 v0, v0
	v_pk_add_f32 v[2:3], v[78:79], v[2:3]
	v_pk_mul_f32 v[6:7], v[6:7], v[10:11]
	v_cndmask_b32_e64 v5, v5, 0, s[54:55]
	v_add_f32_e32 v0, 1.0, v0
	v_pk_mul_f32 v[2:3], v[2:3], v[6:7]
	v_rcp_f32_e32 v6, v0
	v_mul_f32_e32 v0, 0x3d122279, v9
	v_fmaak_f32 v0, v9, v0, 0x3f4c422a
	v_mul_f32_e32 v0, v9, v0
	v_mul_f32_e32 v0, 0xc038aa3b, v0
	v_exp_f32_e32 v0, v0
	v_cndmask_b32_e64 v4, v4, 0, s[54:55]
	v_pk_mul_f32 v[10:11], v[44:45], v[72:73]
	v_cvt_pk_bf16_f32 v2, v2, v3
	v_add_f32_e32 v0, 1.0, v0
	v_rcp_f32_e32 v7, v0
	v_pk_fma_f32 v[4:5], v[4:5], v[68:69], v[10:11]
	v_pk_mul_f32 v[6:7], v[8:9], v[6:7]
	v_pk_fma_f32 v[4:5], v[76:77], v[42:43], v[4:5]
	s_nop 0
	v_pk_add_f32 v[4:5], v[80:81], v[4:5]
	s_nop 0
	v_pk_mul_f32 v[4:5], v[4:5], v[6:7]
	s_nop 0
	v_cvt_pk_bf16_f32 v3, v4, v5
	v_lshlrev_b64 v[4:5], 12, v[134:135]
	v_lshl_add_u64 v[4:5], s[70:71], 0, v[4:5]
	v_lshl_add_u64 v[4:5], v[180:181], 1, v[4:5]
	global_store_dwordx2 v[4:5], v[2:3], off offset:8

; __device__ __forceinline__ unsigned cvt_pk_bf16(float lo, float hi) { f32x2 v = {lo, hi}; bf16x2_t_ b = __builtin_convertvector(v, bf16x2_t_); return __builtin_bit_cast(unsigned, b); }
;     __device__ __forceinline__ void operator()(f32x4 (&acc)[2][2][4][2], const Unit& u, int wr, int wc, int fr, int fq) const {
;     ...
;                 for (int j = 0; j < 8; ++j) {
;                     float Lg = j == 0 ? lg : ag[j == 0 ? 0 : j - 1], Rg = j == 7 ? rg : ag[j == 7 ? 7 : j + 1];
;                     float Lv = j == 0 ? lv : av[j == 0 ? 0 : j - 1], Rv = j == 7 ? rv : av[j == 7 ? 7 : j + 1];
;                     if ((smask >> j) & 1u) { Lg = 0.f; Lv = 0.f; }
;                     if ((emask >> j) & 1u) { Rg = 0.f; Rv = 0.f; }
;                     const float cgv = w0g[i] * Lg + w1g[i] * ag[j] + w2g[i] * Rg + bg[i];
;                     const float cvv = w0v[i] * Lv + w1v[i] * av[j] + w2v[i] * Rv + bv[i];
;                     h[j][i] = gelu_t(cgv) * cvv;
;                 }
;             }
; #pragma unroll
;             for (int j = 0; j < 8; ++j) if ((vmask >> j) & 1u) { u32x2 w; w.x = cvt_pk_bf16(h[j][0], h[j][1]); w.y = cvt_pk_bf16(h[j][2], h[j][3]);
;                 *(u32x2*)(H2 + (size_t)(t0 + j) * 2048 + cg_) = w; }
.LBB0_153:
	v_cndmask_b32_e64 v23, v23, 0, s[50:51]
	v_cndmask_b32_e64 v22, v22, 0, s[50:51]
	v_pk_mul_f32 v[26:27], v[14:15], v[94:95]
	v_cndmask_b32_e64 v19, v19, 0, s[50:51]
	v_pk_fma_f32 v[22:23], v[22:23], v[82:83], v[26:27]
	v_cndmask_b32_e64 v18, v18, 0, s[50:51]
	v_pk_fma_f32 v[22:23], v[6:7], v[86:87], v[22:23]
	v_pk_mul_f32 v[28:29], v[10:11], v[70:71]
	v_pk_add_f32 v[22:23], v[90:91], v[22:23]
	v_pk_fma_f32 v[18:19], v[18:19], v[66:67], v[28:29]
	v_mul_f32_e32 v0, 0x3d122279, v22
	v_fmaak_f32 v0, v22, v0, 0x3f4c422a
	v_mul_f32_e32 v0, v22, v0
	v_mul_f32_e32 v0, 0xc038aa3b, v0
	v_exp_f32_e32 v0, v0
	v_pk_fma_f32 v[18:19], v[2:3], v[74:75], v[18:19]
	v_cndmask_b32_e64 v21, v21, 0, s[50:51]
	v_pk_add_f32 v[18:19], v[78:79], v[18:19]
	v_add_f32_e32 v0, 1.0, v0
	v_rcp_f32_e32 v26, v0
	v_mul_f32_e32 v0, 0x3d122279, v23
	v_fmaak_f32 v0, v23, v0, 0x3f4c422a
	v_mul_f32_e32 v0, v23, v0
	v_mul_f32_e32 v0, 0xc038aa3b, v0
	v_exp_f32_e32 v0, v0
	v_cndmask_b32_e64 v20, v20, 0, s[50:51]
	v_add_f32_e32 v0, 1.0, v0
	v_rcp_f32_e32 v27, v0
	s_nop 0
	v_pk_mul_f32 v[22:23], v[22:23], v[26:27]
	s_nop 0
	v_pk_mul_f32 v[18:19], v[18:19], v[22:23]
	v_cndmask_b32_e64 v23, v25, 0, s[50:51]
	v_cndmask_b32_e64 v22, v24, 0, s[50:51]
	v_pk_mul_f32 v[24:25], v[16:17], v[96:97]
	v_pk_mul_f32 v[26:27], v[12:13], v[72:73]
	v_pk_fma_f32 v[22:23], v[22:23], v[84:85], v[24:25]
	v_pk_fma_f32 v[20:21], v[20:21], v[68:69], v[26:27]
	v_pk_fma_f32 v[22:23], v[8:9], v[88:89], v[22:23]
	v_pk_fma_f32 v[20:21], v[4:5], v[76:77], v[20:21]
	v_pk_add_f32 v[22:23], v[92:93], v[22:23]
	v_pk_add_f32 v[20:21], v[80:81], v[20:21]
	v_mul_f32_e32 v0, 0x3d122279, v22
	v_fmaak_f32 v0, v22, v0, 0x3f4c422a
	v_mul_f32_e32 v0, v22, v0
	v_mul_f32_e32 v0, 0xc038aa3b, v0
	v_exp_f32_e32 v0, v0
	v_cvt_pk_bf16_f32 v18, v18, v19
	v_add_f32_e32 v0, 1.0, v0
	v_rcp_f32_e32 v24, v0
	v_mul_f32_e32 v0, 0x3d122279, v23
	v_fmaak_f32 v0, v23, v0, 0x3f4c422a
	v_mul_f32_e32 v0, v23, v0
	v_mul_f32_e32 v0, 0xc038aa3b, v0
	v_exp_f32_e32 v0, v0
	s_nop 0
	v_add_f32_e32 v0, 1.0, v0
	v_rcp_f32_e32 v25, v0
	s_nop 0
	v_pk_mul_f32 v[22:23], v[22:23], v[24:25]
	s_nop 0
	v_pk_mul_f32 v[20:21], v[20:21], v[22:23]
	s_nop 0
	v_cvt_pk_bf16_f32 v19, v20, v21
	v_lshlrev_b64 v[20:21], 12, v[128:129]
	v_lshl_add_u64 v[20:21], s[70:71], 0, v[20:21]
	v_lshl_add_u64 v[20:21], v[180:181], 1, v[20:21]
	global_store_dwordx2 v[20:21], v[18:19], off offset:8
	s_or_b64 exec, exec, s[0:1]
	s_and_saveexec_b64 s[0:1], s[66:67]
	s_cbranch_execz .LBB0_148
.LBB0_154:
	v_pk_mul_f32 v[20:21], v[6:7], v[94:95]
	v_cndmask_b32_e64 v19, v55, 0, s[52:53]
	v_cndmask_b32_e64 v18, v54, 0, s[52:53]
	v_pk_fma_f32 v[14:15], v[14:15], v[82:83], v[20:21]
	v_pk_mul_f32 v[22:23], v[2:3], v[70:71]
	v_pk_fma_f32 v[14:15], v[18:19], v[86:87], v[14:15]
	v_cndmask_b32_e64 v21, v47, 0, s[52:53]
	v_pk_add_f32 v[14:15], v[90:91], v[14:15]
	v_cndmask_b32_e64 v20, v46, 0, s[52:53]
	v_mul_f32_e32 v0, 0x3d122279, v14
	v_fmaak_f32 v0, v14, v0, 0x3f4c422a
	v_mul_f32_e32 v0, v14, v0
	v_mul_f32_e32 v0, 0xc038aa3b, v0
	v_exp_f32_e32 v0, v0
	v_pk_fma_f32 v[10:11], v[10:11], v[66:67], v[22:23]
	v_add_f32_e32 v0, 1.0, v0
	v_rcp_f32_e32 v18, v0
	v_mul_f32_e32 v0, 0x3d122279, v15
	v_fmaak_f32 v0, v15, v0, 0x3f4c422a
	v_mul_f32_e32 v0, v15, v0
	v_mul_f32_e32 v0, 0xc038aa3b, v0
	v_exp_f32_e32 v0, v0
	v_pk_fma_f32 v[10:11], v[20:21], v[74:75], v[10:11]
	v_pk_mul_f32 v[20:21], v[4:5], v[72:73]
	v_pk_add_f32 v[10:11], v[78:79], v[10:11]
	v_add_f32_e32 v0, 1.0, v0
	v_rcp_f32_e32 v19, v0
	v_pk_fma_f32 v[12:13], v[12:13], v[68:69], v[20:21]
	v_pk_mul_f32 v[14:15], v[14:15], v[18:19]
	v_pk_mul_f32 v[18:19], v[8:9], v[96:97]
	v_pk_mul_f32 v[10:11], v[10:11], v[14:15]
	v_cndmask_b32_e64 v15, v49, 0, s[52:53]
	v_cndmask_b32_e64 v14, v48, 0, s[52:53]
	v_pk_fma_f32 v[16:17], v[16:17], v[84:85], v[18:19]
	v_cndmask_b32_e64 v19, v45, 0, s[52:53]
	v_pk_fma_f32 v[14:15], v[14:15], v[88:89], v[16:17]
	v_cndmask_b32_e64 v18, v44, 0, s[52:53]
	v_pk_add_f32 v[14:15], v[92:93], v[14:15]
	v_pk_fma_f32 v[12:13], v[18:19], v[76:77], v[12:13]
	v_mul_f32_e32 v0, 0x3d122279, v14
	v_fmaak_f32 v0, v14, v0, 0x3f4c422a
	v_mul_f32_e32 v0, v14, v0
	v_mul_f32_e32 v0, 0xc038aa3b, v0
	v_exp_f32_e32 v0, v0
	v_pk_add_f32 v[12:13], v[80:81], v[12:13]
	v_cvt_pk_bf16_f32 v10, v10, v11
	v_add_f32_e32 v0, 1.0, v0
	v_rcp_f32_e32 v16, v0
	v_mul_f32_e32 v0, 0x3d122279, v15
	v_fmaak_f32 v0, v15, v0, 0x3f4c422a
	v_mul_f32_e32 v0, v15, v0
	v_mul_f32_e32 v0, 0xc038aa3b, v0
	v_exp_f32_e32 v0, v0
	s_nop 0
	v_add_f32_e32 v0, 1.0, v0
	v_rcp_f32_e32 v17, v0
	s_nop 0
	v_pk_mul_f32 v[14:15], v[14:15], v[16:17]
	s_nop 0
	v_pk_mul_f32 v[12:13], v[12:13], v[14:15]
	s_nop 0
	v_cvt_pk_bf16_f32 v11, v12, v13
	v_lshlrev_b64 v[12:13], 12, v[132:133]
	v_lshl_add_u64 v[12:13], s[70:71], 0, v[12:13]
	v_lshl_add_u64 v[12:13], v[180:181], 1, v[12:13]
	global_store_dwordx2 v[12:13], v[10:11], off offset:8
	s_or_b64 exec, exec, s[0:1]
	s_and_saveexec_b64 s[0:1], s[76:77]
	s_cbranch_execnz .LBB0_149
	s_branch .LBB0_150

; __device__ __forceinline__ unsigned cvt_pk_bf16(float lo, float hi) { f32x2 v = {lo, hi}; bf16x2_t_ b = __builtin_convertvector(v, bf16x2_t_); return __builtin_bit_cast(unsigned, b); }
; __device__ __forceinline__ float bf_lo(unsigned w) { return __uint_as_float(w << 16); }
; __device__ __forceinline__ float bf_hi(unsigned w) { return __uint_as_float(w & 0xffff0000u); }
;     __device__ __forceinline__ void operator()(f32x4 (&acc)[2][2][4][2], const Unit& u, int wr, int wc, int fr, int fq) const {
;         const int t0 = u.pm * 256 + wr * 64 + fr;
;         const size_t off0 = (size_t)t0 * 1024 + 256 * u.pn + 32 * wc + 8 * fq;
;         const bf16_t* src = (u.part == 0) ? GB : (const bf16_t*)GA;
; #pragma unroll
;         for (int ai = 0; ai < 2; ++ai)
; #pragma unroll
;             for (int m = 0; m < 4; ++m)
; #pragma unroll
;                 for (int bj = 0; bj < 2; ++bj) {
;                     const size_t off = off0 + (size_t)(128 * ai + 16 * m) * 1024 + 128 * bj;
;                     const u32x4 g = *(const u32x4*)(src + off);
;                     const f32x4 s0 = (f32x4){bf_lo(g.x), bf_hi(g.x), bf_lo(g.y), bf_hi(g.y)}, s1 = (f32x4){bf_lo(g.z), bf_hi(g.z), bf_lo(g.w), bf_hi(g.w)};
;                     const f32x4 v0 = acc[ai][bj][m][0] * s0, v1 = acc[ai][bj][m][1] * s1;
;                     if (u.part == 0) { acc[ai][bj][m][0] = v0; acc[ai][bj][m][1] = v1; }
;                     else { u32x4 w; w.x = cvt_pk_bf16(v0.x, v0.y); w.y = cvt_pk_bf16(v0.z, v0.w); w.z = cvt_pk_bf16(v1.x, v1.y); w.w = cvt_pk_bf16(v1.z, v1.w);
;                         *(u32x4*)(GA + off) = w; }
;                 }
.LBB0_209:
	s_lshl_b32 s34, s74, 8
	s_ashr_i32 s35, s34, 31
	s_cmp_lg_u32 s41, 0
	s_cselect_b64 s[56:57], -1, 0
	s_cmp_eq_u32 s41, 0
	v_lshl_add_u32 v2, s40, 8, v173
	s_cselect_b64 s[40:41], -1, 0
	v_readlane_b32 s58, v252, 11
	v_ashrrev_i32_e32 v3, 31, v2
	s_and_b64 vcc, s[40:41], exec
	v_readlane_b32 s59, v252, 12
	v_lshlrev_b64 v[2:3], 10, v[2:3]
	s_cselect_b32 s40, s59, s71
	s_cselect_b32 s41, s58, s70
	v_mov_b32_e32 v47, s35
	v_or_b32_e32 v46, s34, v172
	v_mov_b32_e32 v44, s41
	v_mov_b32_e32 v45, s40
	v_lshl_add_u64 v[84:85], v[2:3], 0, v[46:47]
	v_lshl_add_u64 v[2:3], v[84:85], 1, v[44:45]
	global_load_dwordx4 v[44:47], v[2:3], off
	s_mov_b32 s101, 0
	global_load_dwordx4 v[182:185], v[2:3], off offset:256
	s_mov_b32 s100, 0x8000
	v_lshl_add_u64 v[224:225], v[2:3], 0, s[100:101]
	global_load_dwordx4 v[186:189], v[224:225], off
	global_load_dwordx4 v[196:199], v[224:225], off offset:256
	s_mov_b32 s100, 0x10000
	v_lshl_add_u64 v[224:225], v[2:3], 0, s[100:101]
	global_load_dwordx4 v[200:203], v[224:225], off
	global_load_dwordx4 v[204:207], v[224:225], off offset:256
	s_mov_b32 s100, 0x18000
	v_lshl_add_u64 v[224:225], v[2:3], 0, s[100:101]
	global_load_dwordx4 v[208:211], v[224:225], off
	global_load_dwordx4 v[212:215], v[224:225], off offset:256
	s_mov_b32 s100, 0x40000
	v_lshl_add_u64 v[224:225], v[2:3], 0, s[100:101]
	global_load_dwordx4 v[236:239], v[224:225], off
	global_load_dwordx4 v[240:243], v[224:225], off offset:256
	s_mov_b32 s100, 0x48000
	v_lshl_add_u64 v[224:225], v[2:3], 0, s[100:101]
	global_load_dwordx4 v[248:251], v[224:225], off
	global_load_dwordx4 v[228:231], v[224:225], off offset:256
	v_lshl_add_u64 v[178:179], v[84:85], 1, s[70:71]
	s_waitcnt vmcnt(11)
	v_lshlrev_b32_e32 v48, 16, v44
	v_and_b32_e32 v49, 0xffff0000, v44
	v_lshlrev_b32_e32 v44, 16, v45
	v_and_b32_e32 v45, 0xffff0000, v45
	v_lshlrev_b32_e32 v86, 16, v46
	v_and_b32_e32 v87, 0xffff0000, v46
	v_lshlrev_b32_e32 v46, 16, v47
	v_and_b32_e32 v47, 0xffff0000, v47
	v_pk_mul_f32 v[50:51], v[74:75], v[44:45]
	v_pk_mul_f32 v[48:49], v[72:73], v[48:49]
	v_pk_mul_f32 v[46:47], v[70:71], v[46:47]
	v_pk_mul_f32 v[44:45], v[68:69], v[86:87]
	s_cbranch_vccnz .LBB0_211
	v_cvt_pk_bf16_f32 v48, v48, v49
	v_cvt_pk_bf16_f32 v49, v50, v51
	v_cvt_pk_bf16_f32 v50, v44, v45
	v_cvt_pk_bf16_f32 v51, v46, v47
	global_store_dwordx4 v[178:179], v[48:51], off
	v_mov_b64_e32 v[44:45], v[68:69]
	v_mov_b64_e32 v[46:47], v[70:71]
	v_mov_b64_e32 v[48:49], v[72:73]
	v_mov_b64_e32 v[50:51], v[74:75]
.LBB0_211:
	v_cndmask_b32_e64 v0, 0, 1, s[56:57]
	v_cmp_ne_u32_e64 s[40:41], 1, v0
	s_andn2_b64 vcc, exec, s[56:57]
	s_waitcnt vmcnt(10)
	v_mov_b64_e32 v[68:69], v[182:183]
	v_mov_b64_e32 v[70:71], v[184:185]
	v_lshlrev_b32_e32 v72, 16, v68
	v_and_b32_e32 v73, 0xffff0000, v68
	v_lshlrev_b32_e32 v68, 16, v69
	v_and_b32_e32 v69, 0xffff0000, v69
	v_lshlrev_b32_e32 v86, 16, v70
	v_and_b32_e32 v87, 0xffff0000, v70
	v_lshlrev_b32_e32 v70, 16, v71
	v_and_b32_e32 v71, 0xffff0000, v71
	v_pk_mul_f32 v[74:75], v[162:163], v[68:69]
	v_pk_mul_f32 v[72:73], v[160:161], v[72:73]
	v_pk_mul_f32 v[70:71], v[158:159], v[70:71]
	v_pk_mul_f32 v[68:69], v[156:157], v[86:87]
	s_cbranch_vccnz .LBB0_213
	v_lshlrev_b64 v[84:85], 1, v[84:85]
	v_or_b32_e32 v84, 0x100, v84
	v_cvt_pk_bf16_f32 v72, v72, v73
	v_cvt_pk_bf16_f32 v73, v74, v75
	v_cvt_pk_bf16_f32 v74, v68, v69
	v_cvt_pk_bf16_f32 v75, v70, v71
	v_lshl_add_u64 v[68:69], s[70:71], 0, v[84:85]
	global_store_dwordx4 v[68:69], v[72:75], off
	v_mov_b64_e32 v[68:69], v[156:157]
	v_mov_b64_e32 v[70:71], v[158:159]
	v_mov_b64_e32 v[72:73], v[160:161]
	v_mov_b64_e32 v[74:75], v[162:163]
.LBB0_213:
	v_add_co_u32_e32 v84, vcc, 0x8000, v2
	s_nop 1
	v_addc_co_u32_e32 v85, vcc, 0, v3, vcc
	s_and_b64 vcc, exec, s[40:41]
	s_waitcnt vmcnt(9)
	v_mov_b64_e32 v[84:85], v[186:187]
	v_mov_b64_e32 v[86:87], v[188:189]
	v_lshlrev_b32_e32 v88, 16, v84
	v_and_b32_e32 v89, 0xffff0000, v84
	v_lshlrev_b32_e32 v84, 16, v85
	v_and_b32_e32 v85, 0xffff0000, v85
	v_lshlrev_b32_e32 v116, 16, v86
	v_and_b32_e32 v117, 0xffff0000, v86
	v_lshlrev_b32_e32 v86, 16, v87
	v_and_b32_e32 v87, 0xffff0000, v87
	v_pk_mul_f32 v[90:91], v[106:107], v[84:85]
	v_pk_mul_f32 v[88:89], v[104:105], v[88:89]
	v_pk_mul_f32 v[86:87], v[102:103], v[86:87]
	v_pk_mul_f32 v[84:85], v[100:101], v[116:117]
	s_cbranch_vccnz .LBB0_215
	v_cvt_pk_bf16_f32 v88, v88, v89
	v_cvt_pk_bf16_f32 v89, v90, v91
	v_cvt_pk_bf16_f32 v90, v84, v85
	v_add_co_u32_e32 v84, vcc, 0x8000, v178
	v_cvt_pk_bf16_f32 v91, v86, v87
	s_nop 0
	v_addc_co_u32_e32 v85, vcc, 0, v179, vcc
	global_store_dwordx4 v[84:85], v[88:91], off
	v_mov_b64_e32 v[84:85], v[100:101]
	v_mov_b64_e32 v[86:87], v[102:103]
	v_mov_b64_e32 v[88:89], v[104:105]
	v_mov_b64_e32 v[90:91], v[106:107]
.LBB0_215:
	v_add_co_u32_e32 v100, vcc, 0x8000, v2
	s_nop 1
	v_addc_co_u32_e32 v101, vcc, 0, v3, vcc
	s_and_b64 vcc, exec, s[40:41]
	s_waitcnt vmcnt(8)
	v_mov_b64_e32 v[100:101], v[196:197]
	v_mov_b64_e32 v[102:103], v[198:199]
	v_lshlrev_b32_e32 v104, 16, v100
	v_and_b32_e32 v105, 0xffff0000, v100
	v_lshlrev_b32_e32 v100, 16, v101
	v_and_b32_e32 v101, 0xffff0000, v101
	v_lshlrev_b32_e32 v116, 16, v102
	v_and_b32_e32 v117, 0xffff0000, v102
	v_lshlrev_b32_e32 v102, 16, v103
	v_and_b32_e32 v103, 0xffff0000, v103
	v_pk_mul_f32 v[106:107], v[154:155], v[100:101]
	v_pk_mul_f32 v[104:105], v[152:153], v[104:105]
	v_pk_mul_f32 v[102:103], v[150:151], v[102:103]
	v_pk_mul_f32 v[100:101], v[148:149], v[116:117]
	s_cbranch_vccnz .LBB0_217
	v_cvt_pk_bf16_f32 v104, v104, v105
	v_cvt_pk_bf16_f32 v105, v106, v107
	v_cvt_pk_bf16_f32 v106, v100, v101
	v_add_co_u32_e32 v100, vcc, 0x8000, v178
	v_cvt_pk_bf16_f32 v107, v102, v103
	s_nop 0
	v_addc_co_u32_e32 v101, vcc, 0, v179, vcc
	global_store_dwordx4 v[100:101], v[104:107], off offset:256
	v_mov_b64_e32 v[100:101], v[148:149]
	v_mov_b64_e32 v[102:103], v[150:151]
	v_mov_b64_e32 v[104:105], v[152:153]
	v_mov_b64_e32 v[106:107], v[154:155]
; __device__ __forceinline__ unsigned cvt_pk_bf16(float lo, float hi) { f32x2 v = {lo, hi}; bf16x2_t_ b = __builtin_convertvector(v, bf16x2_t_); return __builtin_bit_cast(unsigned, b); }
; __device__ __forceinline__ float bf_lo(unsigned w) { return __uint_as_float(w << 16); }
; __device__ __forceinline__ float bf_hi(unsigned w) { return __uint_as_float(w & 0xffff0000u); }
;     __device__ __forceinline__ void operator()(f32x4 (&acc)[2][2][4][2], const Unit& u, int wr, int wc, int fr, int fq) const {
;         const int t0 = u.pm * 256 + wr * 64 + fr;
;         const size_t off0 = (size_t)t0 * 1024 + 256 * u.pn + 32 * wc + 8 * fq;
;         const bf16_t* src = (u.part == 0) ? GB : (const bf16_t*)GA;
; #pragma unroll
;         for (int ai = 0; ai < 2; ++ai)
; #pragma unroll
;             for (int m = 0; m < 4; ++m)
; #pragma unroll
;                 for (int bj = 0; bj < 2; ++bj) {
;                     const size_t off = off0 + (size_t)(128 * ai + 16 * m) * 1024 + 128 * bj;
;                     const u32x4 g = *(const u32x4*)(src + off);
;                     const f32x4 s0 = (f32x4){bf_lo(g.x), bf_hi(g.x), bf_lo(g.y), bf_hi(g.y)}, s1 = (f32x4){bf_lo(g.z), bf_hi(g.z), bf_lo(g.w), bf_hi(g.w)};
;                     const f32x4 v0 = acc[ai][bj][m][0] * s0, v1 = acc[ai][bj][m][1] * s1;
;                     if (u.part == 0) { acc[ai][bj][m][0] = v0; acc[ai][bj][m][1] = v1; }
;                     else { u32x4 w; w.x = cvt_pk_bf16(v0.x, v0.y); w.y = cvt_pk_bf16(v0.z, v0.w); w.z = cvt_pk_bf16(v1.x, v1.y); w.w = cvt_pk_bf16(v1.z, v1.w);
;                         *(u32x4*)(GA + off) = w; }
;                 }
.LBB0_217:
	v_add_co_u32_e32 v116, vcc, 0x10000, v2
	s_nop 1
	v_addc_co_u32_e32 v117, vcc, 0, v3, vcc
	s_and_b64 vcc, exec, s[40:41]
	s_waitcnt vmcnt(7)
	v_mov_b64_e32 v[116:117], v[200:201]
	v_mov_b64_e32 v[118:119], v[202:203]
	v_lshlrev_b32_e32 v120, 16, v116
	v_and_b32_e32 v121, 0xffff0000, v116
	v_lshlrev_b32_e32 v116, 16, v117
	v_and_b32_e32 v117, 0xffff0000, v117
	v_lshlrev_b32_e32 v140, 16, v118
	v_and_b32_e32 v141, 0xffff0000, v118
	v_lshlrev_b32_e32 v118, 16, v119
	v_and_b32_e32 v119, 0xffff0000, v119
	v_pk_mul_f32 v[122:123], v[138:139], v[116:117]
	v_pk_mul_f32 v[120:121], v[136:137], v[120:121]
	v_pk_mul_f32 v[118:119], v[134:135], v[118:119]
	v_pk_mul_f32 v[116:117], v[132:133], v[140:141]
	s_cbranch_vccnz .LBB0_219
	v_cvt_pk_bf16_f32 v120, v120, v121
	v_cvt_pk_bf16_f32 v121, v122, v123
	v_cvt_pk_bf16_f32 v122, v116, v117
	v_add_co_u32_e32 v116, vcc, 0x10000, v178
	v_cvt_pk_bf16_f32 v123, v118, v119
	s_nop 0
	v_addc_co_u32_e32 v117, vcc, 0, v179, vcc
	global_store_dwordx4 v[116:117], v[120:123], off
	v_mov_b64_e32 v[116:117], v[132:133]
	v_mov_b64_e32 v[118:119], v[134:135]
	v_mov_b64_e32 v[120:121], v[136:137]
	v_mov_b64_e32 v[122:123], v[138:139]
.LBB0_219:
	v_add_co_u32_e32 v132, vcc, 0x10000, v2
	s_nop 1
	v_addc_co_u32_e32 v133, vcc, 0, v3, vcc
	s_mov_b32 s100, 0x50000
	v_lshl_add_u64 v[224:225], v[2:3], 0, s[100:101]
	global_load_dwordx4 v[182:185], v[224:225], off
	global_load_dwordx4 v[186:189], v[224:225], off offset:256
	s_mov_b32 s100, 0x58000
	v_lshl_add_u64 v[224:225], v[2:3], 0, s[100:101]
	global_load_dwordx4 v[196:199], v[224:225], off
	global_load_dwordx4 v[200:203], v[224:225], off offset:256
	s_and_b64 vcc, exec, s[40:41]
	s_waitcnt vmcnt(10)
	v_mov_b64_e32 v[132:133], v[204:205]
	v_mov_b64_e32 v[134:135], v[206:207]
	v_lshlrev_b32_e32 v136, 16, v132
	v_and_b32_e32 v137, 0xffff0000, v132
	v_lshlrev_b32_e32 v132, 16, v133
	v_and_b32_e32 v133, 0xffff0000, v133
	v_lshlrev_b32_e32 v140, 16, v134
	v_and_b32_e32 v141, 0xffff0000, v134
	v_lshlrev_b32_e32 v134, 16, v135
	v_and_b32_e32 v135, 0xffff0000, v135
	v_pk_mul_f32 v[138:139], v[130:131], v[132:133]
	v_pk_mul_f32 v[136:137], v[128:129], v[136:137]
	v_pk_mul_f32 v[134:135], v[126:127], v[134:135]
	v_pk_mul_f32 v[132:133], v[124:125], v[140:141]
	s_cbranch_vccnz .LBB0_221
	v_cvt_pk_bf16_f32 v136, v136, v137
	v_cvt_pk_bf16_f32 v137, v138, v139
	v_cvt_pk_bf16_f32 v138, v132, v133
	v_add_co_u32_e32 v132, vcc, 0x10000, v178
	v_cvt_pk_bf16_f32 v139, v134, v135
	s_nop 0
	v_addc_co_u32_e32 v133, vcc, 0, v179, vcc
	global_store_dwordx4 v[132:133], v[136:139], off offset:256
	v_mov_b64_e32 v[134:135], v[126:127]
	v_mov_b64_e32 v[132:133], v[124:125]
	v_mov_b64_e32 v[138:139], v[130:131]
	v_mov_b64_e32 v[136:137], v[128:129]
.LBB0_221:
	v_add_co_u32_e32 v124, vcc, 0x18000, v2
	s_nop 1
	v_addc_co_u32_e32 v125, vcc, 0, v3, vcc
	s_and_b64 vcc, exec, s[40:41]
	s_waitcnt vmcnt(9)
	v_mov_b64_e32 v[124:125], v[208:209]
	v_mov_b64_e32 v[126:127], v[210:211]
	v_lshlrev_b32_e32 v128, 16, v124
	v_and_b32_e32 v129, 0xffff0000, v124
	v_lshlrev_b32_e32 v124, 16, v125
	v_and_b32_e32 v125, 0xffff0000, v125
	v_lshlrev_b32_e32 v130, 16, v126
	v_and_b32_e32 v131, 0xffff0000, v126
	v_lshlrev_b32_e32 v126, 16, v127
	v_and_b32_e32 v127, 0xffff0000, v127
	v_pk_mul_f32 v[146:147], v[114:115], v[124:125]
	v_pk_mul_f32 v[144:145], v[112:113], v[128:129]
	v_pk_mul_f32 v[142:143], v[110:111], v[126:127]
	v_pk_mul_f32 v[140:141], v[108:109], v[130:131]
	s_cbranch_vccnz .LBB0_223
	v_cvt_pk_bf16_f32 v124, v144, v145
	v_cvt_pk_bf16_f32 v125, v146, v147
	v_cvt_pk_bf16_f32 v126, v140, v141
	v_cvt_pk_bf16_f32 v127, v142, v143
	v_add_co_u32_e32 v128, vcc, 0x18000, v178
	v_mov_b64_e32 v[142:143], v[110:111]
	v_mov_b64_e32 v[146:147], v[114:115]
	v_addc_co_u32_e32 v129, vcc, 0, v179, vcc
	v_mov_b64_e32 v[140:141], v[108:109]
	v_mov_b64_e32 v[144:145], v[112:113]
	global_store_dwordx4 v[128:129], v[124:127], off
.LBB0_223:
	v_add_co_u32_e32 v108, vcc, 0x18000, v2
	s_nop 1
	v_addc_co_u32_e32 v109, vcc, 0, v3, vcc
	s_and_b64 vcc, exec, s[40:41]
	s_waitcnt vmcnt(8)
	v_mov_b64_e32 v[108:109], v[212:213]
	v_mov_b64_e32 v[110:111], v[214:215]
	v_lshlrev_b32_e32 v112, 16, v108
	v_and_b32_e32 v113, 0xffff0000, v108
	v_lshlrev_b32_e32 v108, 16, v109
	v_and_b32_e32 v109, 0xffff0000, v109
	v_lshlrev_b32_e32 v124, 16, v110
	v_and_b32_e32 v125, 0xffff0000, v110
	v_lshlrev_b32_e32 v110, 16, v111
	v_and_b32_e32 v111, 0xffff0000, v111
	v_pk_mul_f32 v[114:115], v[98:99], v[108:109]
	v_pk_mul_f32 v[112:113], v[96:97], v[112:113]
	v_pk_mul_f32 v[110:111], v[94:95], v[110:111]
	v_pk_mul_f32 v[108:109], v[92:93], v[124:125]
	s_cbranch_vccnz .LBB0_225
	v_cvt_pk_bf16_f32 v112, v112, v113
	v_cvt_pk_bf16_f32 v113, v114, v115
	v_cvt_pk_bf16_f32 v114, v108, v109
	v_add_co_u32_e32 v108, vcc, 0x18000, v178
	v_cvt_pk_bf16_f32 v115, v110, v111
	s_nop 0
	v_addc_co_u32_e32 v109, vcc, 0, v179, vcc
	global_store_dwordx4 v[108:109], v[112:115], off offset:256
	v_mov_b64_e32 v[110:111], v[94:95]
	v_mov_b64_e32 v[108:109], v[92:93]
	v_mov_b64_e32 v[114:115], v[98:99]
	v_mov_b64_e32 v[112:113], v[96:97]
; __device__ __forceinline__ unsigned cvt_pk_bf16(float lo, float hi) { f32x2 v = {lo, hi}; bf16x2_t_ b = __builtin_convertvector(v, bf16x2_t_); return __builtin_bit_cast(unsigned, b); }
; __device__ __forceinline__ float bf_lo(unsigned w) { return __uint_as_float(w << 16); }
; __device__ __forceinline__ float bf_hi(unsigned w) { return __uint_as_float(w & 0xffff0000u); }
;     __device__ __forceinline__ void operator()(f32x4 (&acc)[2][2][4][2], const Unit& u, int wr, int wc, int fr, int fq) const {
;         const int t0 = u.pm * 256 + wr * 64 + fr;
;         const size_t off0 = (size_t)t0 * 1024 + 256 * u.pn + 32 * wc + 8 * fq;
;         const bf16_t* src = (u.part == 0) ? GB : (const bf16_t*)GA;
; #pragma unroll
;         for (int ai = 0; ai < 2; ++ai)
; #pragma unroll
;             for (int m = 0; m < 4; ++m)
; #pragma unroll
;                 for (int bj = 0; bj < 2; ++bj) {
;                     const size_t off = off0 + (size_t)(128 * ai + 16 * m) * 1024 + 128 * bj;
;                     const u32x4 g = *(const u32x4*)(src + off);
;                     const f32x4 s0 = (f32x4){bf_lo(g.x), bf_hi(g.x), bf_lo(g.y), bf_hi(g.y)}, s1 = (f32x4){bf_lo(g.z), bf_hi(g.z), bf_lo(g.w), bf_hi(g.w)};
;                     const f32x4 v0 = acc[ai][bj][m][0] * s0, v1 = acc[ai][bj][m][1] * s1;
;                     if (u.part == 0) { acc[ai][bj][m][0] = v0; acc[ai][bj][m][1] = v1; }
;                     else { u32x4 w; w.x = cvt_pk_bf16(v0.x, v0.y); w.y = cvt_pk_bf16(v0.z, v0.w); w.z = cvt_pk_bf16(v1.x, v1.y); w.w = cvt_pk_bf16(v1.z, v1.w);
;                         *(u32x4*)(GA + off) = w; }
;                 }
.LBB0_225:
	v_add_co_u32_e32 v92, vcc, 0x40000, v2
	s_nop 1
	v_addc_co_u32_e32 v93, vcc, 0, v3, vcc
	s_and_b64 vcc, exec, s[40:41]
	s_waitcnt vmcnt(7)
	v_mov_b64_e32 v[92:93], v[236:237]
	v_mov_b64_e32 v[94:95], v[238:239]
	v_lshlrev_b32_e32 v96, 16, v92
	v_and_b32_e32 v97, 0xffff0000, v92
	v_lshlrev_b32_e32 v92, 16, v93
	v_and_b32_e32 v93, 0xffff0000, v93
	v_lshlrev_b32_e32 v124, 16, v94
	v_and_b32_e32 v125, 0xffff0000, v94
	v_lshlrev_b32_e32 v94, 16, v95
	v_and_b32_e32 v95, 0xffff0000, v95
	v_pk_mul_f32 v[98:99], v[82:83], v[92:93]
	v_pk_mul_f32 v[96:97], v[80:81], v[96:97]
	v_pk_mul_f32 v[94:95], v[78:79], v[94:95]
	v_pk_mul_f32 v[92:93], v[76:77], v[124:125]
	s_cbranch_vccnz .LBB0_227
	v_cvt_pk_bf16_f32 v96, v96, v97
	v_cvt_pk_bf16_f32 v97, v98, v99
	v_cvt_pk_bf16_f32 v98, v92, v93
	v_add_co_u32_e32 v92, vcc, 0x40000, v178
	v_cvt_pk_bf16_f32 v99, v94, v95
	s_nop 0
	v_addc_co_u32_e32 v93, vcc, 0, v179, vcc
	global_store_dwordx4 v[92:93], v[96:99], off
	v_mov_b64_e32 v[94:95], v[78:79]
	v_mov_b64_e32 v[92:93], v[76:77]
	v_mov_b64_e32 v[98:99], v[82:83]
	v_mov_b64_e32 v[96:97], v[80:81]
.LBB0_227:
	v_add_co_u32_e32 v76, vcc, 0x40000, v2
	s_nop 1
	v_addc_co_u32_e32 v77, vcc, 0, v3, vcc
	s_and_b64 vcc, exec, s[40:41]
	s_waitcnt vmcnt(6)
	v_mov_b64_e32 v[76:77], v[240:241]
	v_mov_b64_e32 v[78:79], v[242:243]
	v_lshlrev_b32_e32 v80, 16, v76
	v_and_b32_e32 v81, 0xffff0000, v76
	v_lshlrev_b32_e32 v76, 16, v77
	v_and_b32_e32 v77, 0xffff0000, v77
	v_lshlrev_b32_e32 v124, 16, v78
	v_and_b32_e32 v125, 0xffff0000, v78
	v_lshlrev_b32_e32 v78, 16, v79
	v_and_b32_e32 v79, 0xffff0000, v79
	v_pk_mul_f32 v[82:83], v[66:67], v[76:77]
	v_pk_mul_f32 v[80:81], v[64:65], v[80:81]
	v_pk_mul_f32 v[78:79], v[62:63], v[78:79]
	v_pk_mul_f32 v[76:77], v[60:61], v[124:125]
	s_cbranch_vccnz .LBB0_229
	v_cvt_pk_bf16_f32 v80, v80, v81
	v_cvt_pk_bf16_f32 v81, v82, v83
	v_cvt_pk_bf16_f32 v82, v76, v77
	v_add_co_u32_e32 v76, vcc, 0x40000, v178
	v_cvt_pk_bf16_f32 v83, v78, v79
	s_nop 0
	v_addc_co_u32_e32 v77, vcc, 0, v179, vcc
	global_store_dwordx4 v[76:77], v[80:83], off offset:256
	v_mov_b64_e32 v[78:79], v[62:63]
	v_mov_b64_e32 v[76:77], v[60:61]
	v_mov_b64_e32 v[82:83], v[66:67]
	v_mov_b64_e32 v[80:81], v[64:65]
.LBB0_229:
	v_add_co_u32_e32 v60, vcc, 0x48000, v2
	s_nop 1
	v_addc_co_u32_e32 v61, vcc, 0, v3, vcc
	s_and_b64 vcc, exec, s[40:41]
	s_waitcnt vmcnt(5)
	v_mov_b64_e32 v[60:61], v[248:249]
	v_mov_b64_e32 v[62:63], v[250:251]
	v_lshlrev_b32_e32 v64, 16, v60
	v_and_b32_e32 v65, 0xffff0000, v60
	v_lshlrev_b32_e32 v60, 16, v61
	v_and_b32_e32 v61, 0xffff0000, v61
	v_lshlrev_b32_e32 v66, 16, v62
	v_and_b32_e32 v67, 0xffff0000, v62
	v_lshlrev_b32_e32 v62, 16, v63
	v_and_b32_e32 v63, 0xffff0000, v63
	v_pk_mul_f32 v[130:131], v[58:59], v[60:61]
	v_pk_mul_f32 v[128:129], v[56:57], v[64:65]
	v_pk_mul_f32 v[126:127], v[54:55], v[62:63]
	v_pk_mul_f32 v[124:125], v[52:53], v[66:67]
	s_cbranch_vccnz .LBB0_231
	v_cvt_pk_bf16_f32 v60, v128, v129
	v_cvt_pk_bf16_f32 v61, v130, v131
	v_cvt_pk_bf16_f32 v62, v124, v125
	v_cvt_pk_bf16_f32 v63, v126, v127
	v_add_co_u32_e32 v64, vcc, 0x48000, v178
	v_mov_b64_e32 v[126:127], v[54:55]
	v_mov_b64_e32 v[130:131], v[58:59]
	v_addc_co_u32_e32 v65, vcc, 0, v179, vcc
	v_mov_b64_e32 v[124:125], v[52:53]
	v_mov_b64_e32 v[128:129], v[56:57]
	global_store_dwordx4 v[64:65], v[60:63], off
.LBB0_231:
	v_add_co_u32_e32 v52, vcc, 0x48000, v2
	s_nop 1
	v_addc_co_u32_e32 v53, vcc, 0, v3, vcc
	s_and_b64 vcc, exec, s[40:41]
	s_waitcnt vmcnt(4)
	v_mov_b64_e32 v[52:53], v[228:229]
	v_mov_b64_e32 v[54:55], v[230:231]
	v_lshlrev_b32_e32 v56, 16, v52
	v_and_b32_e32 v57, 0xffff0000, v52
	v_lshlrev_b32_e32 v52, 16, v53
	v_and_b32_e32 v53, 0xffff0000, v53
	v_lshlrev_b32_e32 v60, 16, v54
	v_and_b32_e32 v61, 0xffff0000, v54
	v_lshlrev_b32_e32 v54, 16, v55
	v_and_b32_e32 v55, 0xffff0000, v55
	v_pk_mul_f32 v[58:59], v[42:43], v[52:53]
	v_pk_mul_f32 v[56:57], v[40:41], v[56:57]
	v_pk_mul_f32 v[54:55], v[38:39], v[54:55]
	v_pk_mul_f32 v[52:53], v[36:37], v[60:61]
	s_cbranch_vccnz .LBB0_233
	v_cvt_pk_bf16_f32 v56, v56, v57
	v_cvt_pk_bf16_f32 v57, v58, v59
	v_cvt_pk_bf16_f32 v58, v52, v53
	v_add_co_u32_e32 v52, vcc, 0x48000, v178
	v_cvt_pk_bf16_f32 v59, v54, v55
	s_nop 0
	v_addc_co_u32_e32 v53, vcc, 0, v179, vcc
	global_store_dwordx4 v[52:53], v[56:59], off offset:256
	v_mov_b64_e32 v[54:55], v[38:39]
	v_mov_b64_e32 v[52:53], v[36:37]
	v_mov_b64_e32 v[58:59], v[42:43]
	v_mov_b64_e32 v[56:57], v[40:41]
; __device__ __forceinline__ unsigned cvt_pk_bf16(float lo, float hi) { f32x2 v = {lo, hi}; bf16x2_t_ b = __builtin_convertvector(v, bf16x2_t_); return __builtin_bit_cast(unsigned, b); }
; __device__ __forceinline__ float bf_lo(unsigned w) { return __uint_as_float(w << 16); }
; __device__ __forceinline__ float bf_hi(unsigned w) { return __uint_as_float(w & 0xffff0000u); }
;     __device__ __forceinline__ void operator()(f32x4 (&acc)[2][2][4][2], const Unit& u, int wr, int wc, int fr, int fq) const {
;         const int t0 = u.pm * 256 + wr * 64 + fr;
;         const size_t off0 = (size_t)t0 * 1024 + 256 * u.pn + 32 * wc + 8 * fq;
;         const bf16_t* src = (u.part == 0) ? GB : (const bf16_t*)GA;
; #pragma unroll
;         for (int ai = 0; ai < 2; ++ai)
; #pragma unroll
;             for (int m = 0; m < 4; ++m)
; #pragma unroll
;                 for (int bj = 0; bj < 2; ++bj) {
;                     const size_t off = off0 + (size_t)(128 * ai + 16 * m) * 1024 + 128 * bj;
;                     const u32x4 g = *(const u32x4*)(src + off);
;                     const f32x4 s0 = (f32x4){bf_lo(g.x), bf_hi(g.x), bf_lo(g.y), bf_hi(g.y)}, s1 = (f32x4){bf_lo(g.z), bf_hi(g.z), bf_lo(g.w), bf_hi(g.w)};
;                     const f32x4 v0 = acc[ai][bj][m][0] * s0, v1 = acc[ai][bj][m][1] * s1;
;                     if (u.part == 0) { acc[ai][bj][m][0] = v0; acc[ai][bj][m][1] = v1; }
;                     else { u32x4 w; w.x = cvt_pk_bf16(v0.x, v0.y); w.y = cvt_pk_bf16(v0.z, v0.w); w.z = cvt_pk_bf16(v1.x, v1.y); w.w = cvt_pk_bf16(v1.z, v1.w);
;                         *(u32x4*)(GA + off) = w; }
;                 }
.LBB0_233:
	v_add_co_u32_e32 v36, vcc, 0x50000, v2
	s_nop 1
	v_addc_co_u32_e32 v37, vcc, 0, v3, vcc
	s_and_b64 vcc, exec, s[40:41]
	s_waitcnt vmcnt(3)
	v_mov_b64_e32 v[36:37], v[182:183]
	v_mov_b64_e32 v[38:39], v[184:185]
	v_lshlrev_b32_e32 v40, 16, v36
	v_and_b32_e32 v41, 0xffff0000, v36
	v_lshlrev_b32_e32 v36, 16, v37
	v_and_b32_e32 v37, 0xffff0000, v37
	v_lshlrev_b32_e32 v42, 16, v38
	v_and_b32_e32 v43, 0xffff0000, v38
	v_lshlrev_b32_e32 v38, 16, v39
	v_and_b32_e32 v39, 0xffff0000, v39
	v_pk_mul_f32 v[154:155], v[34:35], v[36:37]
	v_pk_mul_f32 v[152:153], v[32:33], v[40:41]
	v_pk_mul_f32 v[150:151], v[30:31], v[38:39]
	v_pk_mul_f32 v[148:149], v[28:29], v[42:43]
	s_cbranch_vccnz .LBB0_235
	v_cvt_pk_bf16_f32 v36, v152, v153
	v_cvt_pk_bf16_f32 v37, v154, v155
	v_cvt_pk_bf16_f32 v38, v148, v149
	v_cvt_pk_bf16_f32 v39, v150, v151
	v_add_co_u32_e32 v40, vcc, 0x50000, v178
	v_mov_b64_e32 v[150:151], v[30:31]
	v_mov_b64_e32 v[154:155], v[34:35]
	v_addc_co_u32_e32 v41, vcc, 0, v179, vcc
	v_mov_b64_e32 v[148:149], v[28:29]
	v_mov_b64_e32 v[152:153], v[32:33]
	global_store_dwordx4 v[40:41], v[36:39], off
.LBB0_235:
	v_add_co_u32_e32 v28, vcc, 0x50000, v2
	s_nop 1
	v_addc_co_u32_e32 v29, vcc, 0, v3, vcc
	s_and_b64 vcc, exec, s[40:41]
	s_waitcnt vmcnt(2)
	v_mov_b64_e32 v[28:29], v[186:187]
	v_mov_b64_e32 v[30:31], v[188:189]
	v_lshlrev_b32_e32 v32, 16, v28
	v_and_b32_e32 v33, 0xffff0000, v28
	v_lshlrev_b32_e32 v28, 16, v29
	v_and_b32_e32 v29, 0xffff0000, v29
	v_lshlrev_b32_e32 v36, 16, v30
	v_and_b32_e32 v37, 0xffff0000, v30
	v_lshlrev_b32_e32 v30, 16, v31
	v_and_b32_e32 v31, 0xffff0000, v31
	v_pk_mul_f32 v[34:35], v[26:27], v[28:29]
	v_pk_mul_f32 v[32:33], v[24:25], v[32:33]
	v_pk_mul_f32 v[30:31], v[22:23], v[30:31]
	v_pk_mul_f32 v[28:29], v[20:21], v[36:37]
	s_cbranch_vccnz .LBB0_237
	v_cvt_pk_bf16_f32 v32, v32, v33
	v_cvt_pk_bf16_f32 v33, v34, v35
	v_cvt_pk_bf16_f32 v34, v28, v29
	v_add_co_u32_e32 v28, vcc, 0x50000, v178
	v_cvt_pk_bf16_f32 v35, v30, v31
	s_nop 0
	v_addc_co_u32_e32 v29, vcc, 0, v179, vcc
	global_store_dwordx4 v[28:29], v[32:35], off offset:256
	v_mov_b64_e32 v[30:31], v[22:23]
	v_mov_b64_e32 v[28:29], v[20:21]
	v_mov_b64_e32 v[34:35], v[26:27]
	v_mov_b64_e32 v[32:33], v[24:25]
.LBB0_237:
	v_add_co_u32_e32 v20, vcc, 0x58000, v2
	s_nop 1
	v_addc_co_u32_e32 v21, vcc, 0, v3, vcc
	s_and_b64 vcc, exec, s[40:41]
	s_waitcnt vmcnt(1)
	v_mov_b64_e32 v[20:21], v[196:197]
	v_mov_b64_e32 v[22:23], v[198:199]
	v_lshlrev_b32_e32 v24, 16, v20
	v_and_b32_e32 v25, 0xffff0000, v20
	v_lshlrev_b32_e32 v20, 16, v21
	v_and_b32_e32 v21, 0xffff0000, v21
	v_lshlrev_b32_e32 v26, 16, v22
	v_and_b32_e32 v27, 0xffff0000, v22
	v_lshlrev_b32_e32 v22, 16, v23
	v_and_b32_e32 v23, 0xffff0000, v23
	v_pk_mul_f32 v[162:163], v[18:19], v[20:21]
	v_pk_mul_f32 v[160:161], v[16:17], v[24:25]
	v_pk_mul_f32 v[158:159], v[14:15], v[22:23]
	v_pk_mul_f32 v[156:157], v[12:13], v[26:27]
	s_cbranch_vccnz .LBB0_239
	v_cvt_pk_bf16_f32 v20, v160, v161
	v_cvt_pk_bf16_f32 v21, v162, v163
	v_cvt_pk_bf16_f32 v22, v156, v157
	v_cvt_pk_bf16_f32 v23, v158, v159
	v_add_co_u32_e32 v24, vcc, 0x58000, v178
	v_mov_b64_e32 v[158:159], v[14:15]
	v_mov_b64_e32 v[162:163], v[18:19]
	v_addc_co_u32_e32 v25, vcc, 0, v179, vcc
	v_mov_b64_e32 v[156:157], v[12:13]
	v_mov_b64_e32 v[160:161], v[16:17]
	global_store_dwordx4 v[24:25], v[20:23], off
.LBB0_239:
	v_add_co_u32_e32 v2, vcc, 0x58000, v2
	s_nop 1
	v_addc_co_u32_e32 v3, vcc, 0, v3, vcc
	s_and_b64 vcc, exec, s[40:41]
	s_waitcnt vmcnt(0)
	v_mov_b64_e32 v[12:13], v[200:201]
	v_mov_b64_e32 v[14:15], v[202:203]
	v_lshlrev_b32_e32 v2, 16, v12
	v_and_b32_e32 v3, 0xffff0000, v12
	v_lshlrev_b32_e32 v12, 16, v13
	v_and_b32_e32 v13, 0xffff0000, v13
	v_lshlrev_b32_e32 v20, 16, v14
	v_and_b32_e32 v21, 0xffff0000, v14
	v_lshlrev_b32_e32 v14, 16, v15
	v_and_b32_e32 v15, 0xffff0000, v15
	v_pk_mul_f32 v[18:19], v[10:11], v[12:13]
	v_pk_mul_f32 v[16:17], v[8:9], v[2:3]
	v_pk_mul_f32 v[14:15], v[6:7], v[14:15]
	v_pk_mul_f32 v[12:13], v[4:5], v[20:21]
	s_cbranch_vccnz .LBB0_241
	v_add_co_u32_e32 v2, vcc, 0x58000, v178
	v_cvt_pk_bf16_f32 v16, v16, v17
	v_cvt_pk_bf16_f32 v17, v18, v19
	v_cvt_pk_bf16_f32 v18, v12, v13
	v_cvt_pk_bf16_f32 v19, v14, v15
	v_addc_co_u32_e32 v3, vcc, 0, v179, vcc
	global_store_dwordx4 v[2:3], v[16:19], off offset:256
	v_mov_b64_e32 v[14:15], v[6:7]
	v_mov_b64_e32 v[12:13], v[4:5]
	v_mov_b64_e32 v[18:19], v[10:11]
	v_mov_b64_e32 v[16:17], v[8:9]
